# GEMM K-loops: early post-MMA barrier (2 trailing MFMAs at prio 3) on all 8 phases, on top of the trimmed MFMA tails
# speedup vs baseline: 1.0000x; 1.0000x over previous
; #define PG8_STAGE(bufoff, gbase, voff) do { _Pragma("unroll") for (int _i = 0; _i < 2; ++_i) \
;         __builtin_amdgcn_global_load_lds((const unsigned*)((const char*)(gbase) + (voff)[_i]), (LAS unsigned*)(lds + (bufoff) + ldsw + _i * 8192), 16, 0, 0); } while (0)
; #define PG8_LDA(dst, b, h) do { _Pragma("unroll") for (int m = 0; m < 4; ++m) _Pragma("unroll") for (int k = 0; k < 2; ++k) dst[m][k] = *(const LAS bf16x8*)(lds + PG8_SA(b, h) + aoff + m * 2048 + k * 1024); } while (0)
; #define PG8_LDB(dst, b, h) do { _Pragma("unroll") for (int n = 0; n < 2; ++n) _Pragma("unroll") for (int k = 0; k < 2; ++k) dst[n][k] = *(const LAS bf16x8*)(lds + PG8_SB(b, h) + boff + n * 2048 + k * 1024); } while (0)
; #define PG8_WAIT_V(n) asm volatile("s_waitcnt vmcnt(" #n ")" ::: "memory")
; #define PG8_WAIT_L(n) asm volatile("s_waitcnt lgkmcnt(" #n ")" ::: "memory")
; #define PG8_BAR __builtin_amdgcn_s_barrier()
; #define PG8_SCHED __builtin_amdgcn_sched_barrier(0)
; template <class Epi, class Sched, int LD>
; __device__ __forceinline__ void gemm_phase(LAS unsigned char* lds, const Gemm g, const Sched& S, const Epi& E) {
;     ...
;         for (int t = 0; t < nt; t += 2) {
;             const bool last = (t == nt - 2);
;             const char* a1 = cA + (size_t)(t + 1) * kstep;
;             const char* a2 = last ? nA : cA + (size_t)(t + 2) * kstep; const char* b2 = last ? nB : cB + (size_t)(t + 2) * kstep;
;             const char* a3 = a2 + kstep; const char* b3 = b2 + kstep;
;             PG8_LDB(B0, 0, 0); PG8_SCHED; PG8_LDA(At, 0, 0); PG8_STAGE(PG8_SA(1, 1), a1 + hstep, voffA);
;             PG8_WAIT_L(8); PG8_BAR; PG8_WAIT_L(0); PG8_MMA(0, 0, At, B0); PG8_BAR; PG8_SCHED;
;             PG8_LDB(B1, 0, 1); PG8_STAGE(PG8_SB(0, 0), b2, voffB);
;             PG8_BAR; PG8_WAIT_L(0); PG8_MMA(0, 1, At, B1); PG8_BAR;
;             PG8_LDA(At, 0, 1); PG8_STAGE(PG8_SA(0, 0), a2, voffA);
;             PG8_BAR; PG8_WAIT_L(0); PG8_MMA(1, 0, At, B0); PG8_BAR; PG8_SCHED;
;             PG8_STAGE(PG8_SB(0, 1), b2 + hstep, voffB);
;             PG8_WAIT_V(6); PG8_BAR; PG8_MMA(1, 1, At, B1); PG8_BAR;
;             PG8_LDB(B0, 1, 0); PG8_SCHED; PG8_LDA(At, 1, 0); PG8_STAGE(PG8_SA(0, 1), a2 + hstep, voffA);
;             PG8_WAIT_L(8); PG8_BAR; PG8_WAIT_L(0); PG8_MMA(0, 0, At, B0); PG8_BAR; PG8_SCHED;
.LBB0_58:
	s_add_i32 s71, s4, 2
	s_add_u32 s48, s46, 0x4000
	s_addc_u32 s5, s47, 0
	s_cmp_eq_u32 s68, s4
	s_cselect_b32 s4, s42, s48
	s_cselect_b32 s5, s43, s5
	s_cselect_b32 s48, s44, s69
	s_cselect_b32 s49, s45, s70
	s_add_u32 s50, s4, 0x8000
	s_addc_u32 s51, s5, 0
	s_add_i32 s72, 0, 0x10000
	s_add_i32 m0, s39, 0xc000
	ds_read_b128 v[180:183], v148
	ds_read_b128 v[184:187], v148 offset:1024
	ds_read_b128 v[188:191], v148 offset:2048
	ds_read_b128 v[192:195], v148 offset:3072
	ds_read_b128 v[196:199], v148 offset:4096
	ds_read_b128 v[200:203], v148 offset:5120
	ds_read_b128 v[204:207], v148 offset:6144
	ds_read_b128 v[208:211], v148 offset:7168
	global_load_lds_dwordx4 v132, s[46:47]
	s_add_i32 m0, s39, 0xe000
	s_nop 0
	global_load_lds_dwordx4 v138, s[46:47]
	s_waitcnt lgkmcnt(8)
	s_barrier
	s_waitcnt lgkmcnt(0)
	s_setprio 0
	v_mfma_f32_16x16x32_bf16 v[128:131], v[140:143], v[180:183], v[128:131]
	v_mfma_f32_16x16x32_bf16 v[124:127], v[154:157], v[180:183], v[124:127]
	v_mfma_f32_16x16x32_bf16 v[112:115], v[140:143], v[188:191], v[112:115]
	v_mfma_f32_16x16x32_bf16 v[108:111], v[154:157], v[188:191], v[108:111]
	v_mfma_f32_16x16x32_bf16 v[96:99], v[140:143], v[196:199], v[96:99]
	v_mfma_f32_16x16x32_bf16 v[92:95], v[154:157], v[196:199], v[92:95]
	v_mfma_f32_16x16x32_bf16 v[80:83], v[140:143], v[204:207], v[80:83]
	v_mfma_f32_16x16x32_bf16 v[76:79], v[154:157], v[204:207], v[76:79]
	v_mfma_f32_16x16x32_bf16 v[128:131], v[150:153], v[184:187], v[128:131]
	v_mfma_f32_16x16x32_bf16 v[124:127], v[176:179], v[184:187], v[124:127]
	v_mfma_f32_16x16x32_bf16 v[112:115], v[150:153], v[192:195], v[112:115]
	v_mfma_f32_16x16x32_bf16 v[108:111], v[176:179], v[192:195], v[108:111]
	v_mfma_f32_16x16x32_bf16 v[96:99], v[150:153], v[200:203], v[96:99]
	v_mfma_f32_16x16x32_bf16 v[92:95], v[176:179], v[200:203], v[92:95]
	s_barrier
	s_setprio 3
	v_mfma_f32_16x16x32_bf16 v[80:83], v[150:153], v[208:211], v[80:83]
	v_mfma_f32_16x16x32_bf16 v[76:79], v[176:179], v[208:211], v[76:79]
	s_setprio 2
	s_add_i32 s74, 0, 0x14000
	s_add_i32 s72, s72, s29
	ds_read_b128 v[212:215], v228 offset:16384
	ds_read_b128 v[216:219], v228 offset:17408
	ds_read_b128 v[220:223], v228 offset:18432
	ds_read_b128 v[224:227], v228 offset:19456
	s_mov_b32 m0, s72
	s_nop 0
	global_load_lds_dwordx4 v132, s[48:49]
	s_add_i32 m0, s72, 0x2000
	s_nop 0
	global_load_lds_dwordx4 v138, s[48:49]
	s_barrier
	s_waitcnt lgkmcnt(0)
	s_setprio 0
	v_mfma_f32_16x16x32_bf16 v[120:123], v[212:215], v[180:183], v[120:123]
	v_mfma_f32_16x16x32_bf16 v[116:119], v[220:223], v[180:183], v[116:119]
	v_mfma_f32_16x16x32_bf16 v[104:107], v[212:215], v[188:191], v[104:107]
	v_mfma_f32_16x16x32_bf16 v[100:103], v[220:223], v[188:191], v[100:103]
	v_mfma_f32_16x16x32_bf16 v[88:91], v[212:215], v[196:199], v[88:91]
	v_mfma_f32_16x16x32_bf16 v[84:87], v[220:223], v[196:199], v[84:87]
	v_mfma_f32_16x16x32_bf16 v[72:75], v[212:215], v[204:207], v[72:75]
	v_mfma_f32_16x16x32_bf16 v[68:71], v[220:223], v[204:207], v[68:71]
	v_mfma_f32_16x16x32_bf16 v[120:123], v[216:219], v[184:187], v[120:123]
	v_mfma_f32_16x16x32_bf16 v[116:119], v[224:227], v[184:187], v[116:119]
	v_mfma_f32_16x16x32_bf16 v[104:107], v[216:219], v[192:195], v[104:107]
	v_mfma_f32_16x16x32_bf16 v[100:103], v[224:227], v[192:195], v[100:103]
	v_mfma_f32_16x16x32_bf16 v[88:91], v[216:219], v[200:203], v[88:91]
	v_mfma_f32_16x16x32_bf16 v[84:87], v[224:227], v[200:203], v[84:87]
	s_barrier
	s_setprio 3
	v_mfma_f32_16x16x32_bf16 v[72:75], v[216:219], v[208:211], v[72:75]
	v_mfma_f32_16x16x32_bf16 v[68:71], v[224:227], v[208:211], v[68:71]
	s_setprio 2
	s_mov_b32 m0, s39
	ds_read_b128 v[180:183], v148 offset:16384
	ds_read_b128 v[184:187], v148 offset:17408
	ds_read_b128 v[188:191], v148 offset:18432
	ds_read_b128 v[192:195], v148 offset:19456
	ds_read_b128 v[196:199], v148 offset:20480
	ds_read_b128 v[200:203], v148 offset:21504
	ds_read_b128 v[204:207], v148 offset:22528
	ds_read_b128 v[208:211], v148 offset:23552
	global_load_lds_dwordx4 v132, s[4:5]
	s_mov_b32 m0, s52
	s_nop 0
	global_load_lds_dwordx4 v138, s[4:5]
	s_waitcnt vmcnt(10)
	s_barrier
	s_waitcnt lgkmcnt(0)
	s_setprio 0
	v_mfma_f32_16x16x32_bf16 v[64:67], v[140:143], v[180:183], v[64:67]
	v_mfma_f32_16x16x32_bf16 v[60:63], v[154:157], v[180:183], v[60:63]
	v_mfma_f32_16x16x32_bf16 v[48:51], v[140:143], v[188:191], v[48:51]
	v_mfma_f32_16x16x32_bf16 v[44:47], v[154:157], v[188:191], v[44:47]
	v_mfma_f32_16x16x32_bf16 v[32:35], v[140:143], v[196:199], v[32:35]
	v_mfma_f32_16x16x32_bf16 v[28:31], v[154:157], v[196:199], v[28:31]
	v_mfma_f32_16x16x32_bf16 v[16:19], v[140:143], v[204:207], v[16:19]
	v_mfma_f32_16x16x32_bf16 v[12:15], v[154:157], v[204:207], v[12:15]
	v_mfma_f32_16x16x32_bf16 v[64:67], v[150:153], v[184:187], v[64:67]
	v_mfma_f32_16x16x32_bf16 v[60:63], v[176:179], v[184:187], v[60:63]
	v_mfma_f32_16x16x32_bf16 v[48:51], v[150:153], v[192:195], v[48:51]
	v_mfma_f32_16x16x32_bf16 v[44:47], v[176:179], v[192:195], v[44:47]
	v_mfma_f32_16x16x32_bf16 v[32:35], v[150:153], v[200:203], v[32:35]
	v_mfma_f32_16x16x32_bf16 v[28:31], v[176:179], v[200:203], v[28:31]
	s_barrier
	s_setprio 3
	v_mfma_f32_16x16x32_bf16 v[16:19], v[150:153], v[208:211], v[16:19]
	v_mfma_f32_16x16x32_bf16 v[12:15], v[176:179], v[208:211], v[12:15]
	s_setprio 2
	ds_read_b128 v[140:143], v228 offset:32768
	ds_read_b128 v[150:153], v228 offset:33792
	ds_read_b128 v[154:157], v228 offset:34816
	ds_read_b128 v[176:179], v228 offset:35840
	s_add_u32 s72, s48, 0x4000
	s_addc_u32 s73, s49, 0
	s_add_i32 s74, s74, s29
	s_mov_b32 m0, s74
	s_nop 0
	global_load_lds_dwordx4 v132, s[72:73]
	s_add_i32 m0, s74, 0x2000
	s_nop 0
	global_load_lds_dwordx4 v138, s[72:73]
	s_waitcnt vmcnt(6)
	s_barrier
; #define PG8_STAGE(bufoff, gbase, voff) do { _Pragma("unroll") for (int _i = 0; _i < 2; ++_i) \
;         __builtin_amdgcn_global_load_lds((const unsigned*)((const char*)(gbase) + (voff)[_i]), (LAS unsigned*)(lds + (bufoff) + ldsw + _i * 8192), 16, 0, 0); } while (0)
; #define PG8_LDA(dst, b, h) do { _Pragma("unroll") for (int m = 0; m < 4; ++m) _Pragma("unroll") for (int k = 0; k < 2; ++k) dst[m][k] = *(const LAS bf16x8*)(lds + PG8_SA(b, h) + aoff + m * 2048 + k * 1024); } while (0)
; #define PG8_LDB(dst, b, h) do { _Pragma("unroll") for (int n = 0; n < 2; ++n) _Pragma("unroll") for (int k = 0; k < 2; ++k) dst[n][k] = *(const LAS bf16x8*)(lds + PG8_SB(b, h) + boff + n * 2048 + k * 1024); } while (0)
; #define PG8_MMA(ai, bj, At, Bt) do { __builtin_amdgcn_s_setprio(1); _Pragma("unroll") for (int m = 0; m < 4; ++m) _Pragma("unroll") for (int n = 0; n < 2; ++n) _Pragma("unroll") for (int k = 0; k < 2; ++k) \
;         acc[ai][bj][m][n] = __builtin_amdgcn_mfma_f32_16x16x32_bf16(Bt[n][k], At[m][k], acc[ai][bj][m][n], 0, 0, 0); __builtin_amdgcn_s_setprio(0); } while (0)
; #define PG8_WAIT_V(n) asm volatile("s_waitcnt vmcnt(" #n ")" ::: "memory")
; #define PG8_WAIT_L(n) asm volatile("s_waitcnt lgkmcnt(" #n ")" ::: "memory")
; #define PG8_BAR __builtin_amdgcn_s_barrier()
; #define PG8_SCHED __builtin_amdgcn_sched_barrier(0)
; template <class Epi, class Sched, int LD>
; __device__ __forceinline__ void gemm_phase(LAS unsigned char* lds, const Gemm g, const Sched& S, const Epi& E) {
;     ...
;             PG8_BAR; PG8_WAIT_L(0); PG8_MMA(1, 0, At, B0); PG8_BAR; PG8_SCHED;
;             PG8_STAGE(PG8_SB(0, 1), b2 + hstep, voffB);
;             PG8_WAIT_V(6); PG8_BAR; PG8_MMA(1, 1, At, B1); PG8_BAR;
;             PG8_LDB(B0, 1, 0); PG8_SCHED; PG8_LDA(At, 1, 0); PG8_STAGE(PG8_SA(0, 1), a2 + hstep, voffA);
;             PG8_WAIT_L(8); PG8_BAR; PG8_WAIT_L(0); PG8_MMA(0, 0, At, B0); PG8_BAR; PG8_SCHED;
;             PG8_LDB(B1, 1, 1); PG8_STAGE(PG8_SB(1, 0), b3, voffB);
;             PG8_BAR; PG8_WAIT_L(0); PG8_MMA(0, 1, At, B1); PG8_BAR;
;             PG8_LDA(At, 1, 1); PG8_STAGE(PG8_SA(1, 0), a3, voffA);
;             PG8_BAR; PG8_WAIT_L(0); PG8_MMA(1, 0, At, B0); PG8_BAR; PG8_SCHED;
	s_setprio 0
	v_mfma_f32_16x16x32_bf16 v[56:59], v[212:215], v[180:183], v[56:59]
	v_mfma_f32_16x16x32_bf16 v[52:55], v[220:223], v[180:183], v[52:55]
	v_mfma_f32_16x16x32_bf16 v[40:43], v[212:215], v[188:191], v[40:43]
	v_mfma_f32_16x16x32_bf16 v[36:39], v[220:223], v[188:191], v[36:39]
	v_mfma_f32_16x16x32_bf16 v[24:27], v[212:215], v[196:199], v[24:27]
	v_mfma_f32_16x16x32_bf16 v[20:23], v[220:223], v[196:199], v[20:23]
	v_mfma_f32_16x16x32_bf16 v[8:11], v[212:215], v[204:207], v[8:11]
	v_mfma_f32_16x16x32_bf16 v[4:7], v[220:223], v[204:207], v[4:7]
	v_mfma_f32_16x16x32_bf16 v[56:59], v[216:219], v[184:187], v[56:59]
	v_mfma_f32_16x16x32_bf16 v[52:55], v[224:227], v[184:187], v[52:55]
	v_mfma_f32_16x16x32_bf16 v[40:43], v[216:219], v[192:195], v[40:43]
	v_mfma_f32_16x16x32_bf16 v[36:39], v[224:227], v[192:195], v[36:39]
	v_mfma_f32_16x16x32_bf16 v[24:27], v[216:219], v[200:203], v[24:27]
	v_mfma_f32_16x16x32_bf16 v[20:23], v[224:227], v[200:203], v[20:23]
	s_barrier
	s_setprio 3
	v_mfma_f32_16x16x32_bf16 v[8:11], v[216:219], v[208:211], v[8:11]
	v_mfma_f32_16x16x32_bf16 v[4:7], v[224:227], v[208:211], v[4:7]
	s_setprio 2
	s_add_i32 s72, 0, 0x18000
	s_add_u32 s4, s4, 0x4000
	s_addc_u32 s5, s5, 0
	s_mov_b32 m0, s53
	ds_read_b128 v[180:183], v148 offset:32768
	ds_read_b128 v[184:187], v148 offset:33792
	ds_read_b128 v[188:191], v148 offset:34816
	ds_read_b128 v[192:195], v148 offset:35840
	ds_read_b128 v[196:199], v148 offset:36864
	ds_read_b128 v[200:203], v148 offset:37888
	ds_read_b128 v[204:207], v148 offset:38912
	ds_read_b128 v[208:211], v148 offset:39936
	global_load_lds_dwordx4 v132, s[4:5]
	s_mov_b32 m0, s54
	s_nop 0
	global_load_lds_dwordx4 v138, s[4:5]
	s_waitcnt lgkmcnt(8)
	s_barrier
	s_waitcnt lgkmcnt(0)
	s_setprio 0
	v_mfma_f32_16x16x32_bf16 v[128:131], v[140:143], v[180:183], v[128:131]
	v_mfma_f32_16x16x32_bf16 v[124:127], v[154:157], v[180:183], v[124:127]
	v_mfma_f32_16x16x32_bf16 v[112:115], v[140:143], v[188:191], v[112:115]
	v_mfma_f32_16x16x32_bf16 v[108:111], v[154:157], v[188:191], v[108:111]
	v_mfma_f32_16x16x32_bf16 v[96:99], v[140:143], v[196:199], v[96:99]
	v_mfma_f32_16x16x32_bf16 v[92:95], v[154:157], v[196:199], v[92:95]
	v_mfma_f32_16x16x32_bf16 v[80:83], v[140:143], v[204:207], v[80:83]
	v_mfma_f32_16x16x32_bf16 v[76:79], v[154:157], v[204:207], v[76:79]
	v_mfma_f32_16x16x32_bf16 v[128:131], v[150:153], v[184:187], v[128:131]
	v_mfma_f32_16x16x32_bf16 v[124:127], v[176:179], v[184:187], v[124:127]
	v_mfma_f32_16x16x32_bf16 v[112:115], v[150:153], v[192:195], v[112:115]
	v_mfma_f32_16x16x32_bf16 v[108:111], v[176:179], v[192:195], v[108:111]
	v_mfma_f32_16x16x32_bf16 v[96:99], v[150:153], v[200:203], v[96:99]
	v_mfma_f32_16x16x32_bf16 v[92:95], v[176:179], v[200:203], v[92:95]
	s_barrier
	s_setprio 3
	v_mfma_f32_16x16x32_bf16 v[80:83], v[150:153], v[208:211], v[80:83]
	v_mfma_f32_16x16x32_bf16 v[76:79], v[176:179], v[208:211], v[76:79]
	s_setprio 2
	s_add_i32 s73, 0, 0x1c000
	s_add_u32 s4, s48, 0x8000
	s_addc_u32 s5, s49, 0
	s_add_i32 s72, s72, s29
	ds_read_b128 v[212:215], v228 offset:49152
	ds_read_b128 v[216:219], v228 offset:50176
	ds_read_b128 v[220:223], v228 offset:51200
	ds_read_b128 v[224:227], v228 offset:52224
	s_mov_b32 m0, s72
	s_nop 0
	global_load_lds_dwordx4 v132, s[4:5]
	s_add_i32 m0, s72, 0x2000
	s_nop 0
	global_load_lds_dwordx4 v138, s[4:5]
	s_barrier
	s_waitcnt lgkmcnt(0)
	s_setprio 0
	v_mfma_f32_16x16x32_bf16 v[120:123], v[212:215], v[180:183], v[120:123]
	v_mfma_f32_16x16x32_bf16 v[116:119], v[220:223], v[180:183], v[116:119]
	v_mfma_f32_16x16x32_bf16 v[104:107], v[212:215], v[188:191], v[104:107]
	v_mfma_f32_16x16x32_bf16 v[100:103], v[220:223], v[188:191], v[100:103]
	v_mfma_f32_16x16x32_bf16 v[88:91], v[212:215], v[196:199], v[88:91]
	v_mfma_f32_16x16x32_bf16 v[84:87], v[220:223], v[196:199], v[84:87]
	v_mfma_f32_16x16x32_bf16 v[72:75], v[212:215], v[204:207], v[72:75]
	v_mfma_f32_16x16x32_bf16 v[68:71], v[220:223], v[204:207], v[68:71]
	v_mfma_f32_16x16x32_bf16 v[120:123], v[216:219], v[184:187], v[120:123]
	v_mfma_f32_16x16x32_bf16 v[116:119], v[224:227], v[184:187], v[116:119]
	v_mfma_f32_16x16x32_bf16 v[104:107], v[216:219], v[192:195], v[104:107]
	v_mfma_f32_16x16x32_bf16 v[100:103], v[224:227], v[192:195], v[100:103]
	v_mfma_f32_16x16x32_bf16 v[88:91], v[216:219], v[200:203], v[88:91]
	v_mfma_f32_16x16x32_bf16 v[84:87], v[224:227], v[200:203], v[84:87]
	s_barrier
	s_setprio 3
	v_mfma_f32_16x16x32_bf16 v[72:75], v[216:219], v[208:211], v[72:75]
	v_mfma_f32_16x16x32_bf16 v[68:71], v[224:227], v[208:211], v[68:71]
	s_setprio 2
	s_mov_b32 m0, s55
	ds_read_b128 v[180:183], v148 offset:49152
	ds_read_b128 v[184:187], v148 offset:50176
	ds_read_b128 v[188:191], v148 offset:51200
	ds_read_b128 v[192:195], v148 offset:52224
	ds_read_b128 v[196:199], v148 offset:53248
	ds_read_b128 v[200:203], v148 offset:54272
	ds_read_b128 v[204:207], v148 offset:55296
	ds_read_b128 v[208:211], v148 offset:56320
	global_load_lds_dwordx4 v132, s[50:51]
	s_mov_b32 m0, s56
	s_nop 0
	global_load_lds_dwordx4 v138, s[50:51]
	s_waitcnt vmcnt(10)
	s_barrier
	s_waitcnt lgkmcnt(0)
	s_setprio 0
	v_mfma_f32_16x16x32_bf16 v[64:67], v[140:143], v[180:183], v[64:67]
	v_mfma_f32_16x16x32_bf16 v[60:63], v[154:157], v[180:183], v[60:63]
	v_mfma_f32_16x16x32_bf16 v[48:51], v[140:143], v[188:191], v[48:51]
	v_mfma_f32_16x16x32_bf16 v[44:47], v[154:157], v[188:191], v[44:47]
	v_mfma_f32_16x16x32_bf16 v[32:35], v[140:143], v[196:199], v[32:35]
	v_mfma_f32_16x16x32_bf16 v[28:31], v[154:157], v[196:199], v[28:31]
	v_mfma_f32_16x16x32_bf16 v[16:19], v[140:143], v[204:207], v[16:19]
	v_mfma_f32_16x16x32_bf16 v[12:15], v[154:157], v[204:207], v[12:15]
	v_mfma_f32_16x16x32_bf16 v[64:67], v[150:153], v[184:187], v[64:67]
	v_mfma_f32_16x16x32_bf16 v[60:63], v[176:179], v[184:187], v[60:63]
	v_mfma_f32_16x16x32_bf16 v[48:51], v[150:153], v[192:195], v[48:51]
	v_mfma_f32_16x16x32_bf16 v[44:47], v[176:179], v[192:195], v[44:47]
	v_mfma_f32_16x16x32_bf16 v[32:35], v[150:153], v[200:203], v[32:35]
	v_mfma_f32_16x16x32_bf16 v[28:31], v[176:179], v[200:203], v[28:31]
	s_barrier
; #define PG8_STAGE(bufoff, gbase, voff) do { _Pragma("unroll") for (int _i = 0; _i < 2; ++_i) \
;         __builtin_amdgcn_global_load_lds((const unsigned*)((const char*)(gbase) + (voff)[_i]), (LAS unsigned*)(lds + (bufoff) + ldsw + _i * 8192), 16, 0, 0); } while (0)
; #define PG8_MMA(ai, bj, At, Bt) do { __builtin_amdgcn_s_setprio(1); _Pragma("unroll") for (int m = 0; m < 4; ++m) _Pragma("unroll") for (int n = 0; n < 2; ++n) _Pragma("unroll") for (int k = 0; k < 2; ++k) \
;         acc[ai][bj][m][n] = __builtin_amdgcn_mfma_f32_16x16x32_bf16(Bt[n][k], At[m][k], acc[ai][bj][m][n], 0, 0, 0); __builtin_amdgcn_s_setprio(0); } while (0)
; #define PG8_WAIT_V(n) asm volatile("s_waitcnt vmcnt(" #n ")" ::: "memory")
; #define PG8_BAR __builtin_amdgcn_s_barrier()
;     __device__ __forceinline__ void operator()(const f32x4 (&acc)[2][2][4][2], const Unit& u, int wr, int wc, int fr, int fq) const {
;     ...
;         } else {
;             float* base = PART + (size_t)u.part * (512 * 2048);
; #pragma unroll
;             for (int ai = 0; ai < 2; ++ai)
; #pragma unroll
;                 for (int m = 0; m < 4; ++m) {
;                     float* rowp = base + (size_t)(row0 - 8192 + ai * HALF + m * 16) * D_MODEL + col0;
; #pragma unroll
;                     for (int bj = 0; bj < 2; ++bj)
; #pragma unroll
;                         for (int n = 0; n < 2; ++n) *(f32x4*)(rowp + bj * HALF + n * 16) = acc[ai][bj][m][n];
;                 }
; template <class Epi, class Sched, int LD>
; __device__ __forceinline__ void gemm_phase(LAS unsigned char* lds, const Gemm g, const Sched& S, const Epi& E) {
;     ...
;             PG8_STAGE(PG8_SB(1, 1), b3 + hstep, voffB);
;             PG8_WAIT_V(6); PG8_BAR; PG8_MMA(1, 1, At, B1); PG8_BAR;
;         }
	s_setprio 3
	v_mfma_f32_16x16x32_bf16 v[16:19], v[150:153], v[208:211], v[16:19]
	v_mfma_f32_16x16x32_bf16 v[12:15], v[176:179], v[208:211], v[12:15]
	s_setprio 2
	ds_read_b128 v[140:143], v228
	ds_read_b128 v[150:153], v228 offset:1024
	ds_read_b128 v[154:157], v228 offset:2048
	ds_read_b128 v[176:179], v228 offset:3072
	s_add_u32 s4, s48, 0xc000
	s_addc_u32 s5, s49, 0
	s_add_i32 s48, s73, s29
	s_mov_b32 m0, s48
	s_nop 0
	global_load_lds_dwordx4 v132, s[4:5]
	s_add_i32 m0, s48, 0x2000
	s_nop 0
	global_load_lds_dwordx4 v138, s[4:5]
	s_waitcnt vmcnt(6)
	s_barrier
	s_setprio 0
	v_mfma_f32_16x16x32_bf16 v[56:59], v[212:215], v[180:183], v[56:59]
	v_mfma_f32_16x16x32_bf16 v[52:55], v[220:223], v[180:183], v[52:55]
	v_mfma_f32_16x16x32_bf16 v[40:43], v[212:215], v[188:191], v[40:43]
	v_mfma_f32_16x16x32_bf16 v[36:39], v[220:223], v[188:191], v[36:39]
	v_mfma_f32_16x16x32_bf16 v[24:27], v[212:215], v[196:199], v[24:27]
	v_mfma_f32_16x16x32_bf16 v[20:23], v[220:223], v[196:199], v[20:23]
	v_mfma_f32_16x16x32_bf16 v[8:11], v[212:215], v[204:207], v[8:11]
	v_mfma_f32_16x16x32_bf16 v[4:7], v[220:223], v[204:207], v[4:7]
	v_mfma_f32_16x16x32_bf16 v[56:59], v[216:219], v[184:187], v[56:59]
	v_mfma_f32_16x16x32_bf16 v[52:55], v[224:227], v[184:187], v[52:55]
	v_mfma_f32_16x16x32_bf16 v[40:43], v[216:219], v[192:195], v[40:43]
	v_mfma_f32_16x16x32_bf16 v[36:39], v[224:227], v[192:195], v[36:39]
	v_mfma_f32_16x16x32_bf16 v[24:27], v[216:219], v[200:203], v[24:27]
	v_mfma_f32_16x16x32_bf16 v[20:23], v[224:227], v[200:203], v[20:23]
	s_barrier
	s_setprio 3
	v_mfma_f32_16x16x32_bf16 v[8:11], v[216:219], v[208:211], v[8:11]
	v_mfma_f32_16x16x32_bf16 v[4:7], v[224:227], v[208:211], v[4:7]
	s_setprio 2
	s_add_u32 s46, s46, 0x10000
	s_addc_u32 s47, s47, 0
	s_add_u32 s69, s69, 0x10000
	s_addc_u32 s70, s70, 0
	s_cmp_ge_i32 s71, s65
	s_mov_b32 s4, s71
	s_cbranch_scc0 .LBB0_58
	s_setprio 0
	v_lshl_add_u32 v142, s67, 8, v137
	v_lshl_or_b32 v140, s66, 8, v147
	s_mov_b64 s[4:5], -1
	s_cmp_gt_i32 s18, -1
	v_ashrrev_i32_e32 v141, 31, v140
	v_ashrrev_i32_e32 v143, 31, v142
	s_cbranch_scc0 .LBB0_61
	s_lshl_b64 s[4:5], s[18:19], 22
	v_readlane_b32 s18, v252, 10
	s_add_u32 s4, s18, s4
	v_readlane_b32 s18, v252, 11
	s_addc_u32 s5, s18, s5
	v_lshl_add_u64 v[144:145], v[140:141], 2, s[4:5]
	v_lshlrev_b64 v[150:151], 13, v[142:143]
	s_brev_b32 s4, 63
	v_lshl_add_u64 v[144:145], v[144:145], 0, v[150:151]
	s_mov_b32 s5, -1
	v_lshl_add_u64 v[150:151], v[144:145], 0, s[4:5]
	s_brev_b32 s4, 63
	v_add_co_u32_e32 v152, vcc, s4, v144
	s_mov_b32 s4, 0xfc020000
	s_nop 0
	v_addc_co_u32_e32 v153, vcc, -1, v145, vcc
	s_mov_b32 s5, -1
	global_store_dwordx4 v[152:153], v[128:131], off
	global_store_dwordx4 v[150:151], v[124:127], off offset:64
	global_store_dwordx4 v[150:151], v[120:123], off offset:512
	global_store_dwordx4 v[150:151], v[116:119], off offset:576
	v_lshl_add_u64 v[150:151], v[144:145], 0, s[4:5]
	s_mov_b32 s4, 0xfc020000
	v_add_co_u32_e32 v152, vcc, s4, v144
	s_mov_b32 s4, 0xfc040000
	s_nop 0
	v_addc_co_u32_e32 v153, vcc, -1, v145, vcc
	s_mov_b32 s5, -1
	global_store_dwordx4 v[152:153], v[112:115], off
	global_store_dwordx4 v[150:151], v[108:111], off offset:64
	global_store_dwordx4 v[150:151], v[104:107], off offset:512
	global_store_dwordx4 v[150:151], v[100:103], off offset:576
	v_lshl_add_u64 v[150:151], v[144:145], 0, s[4:5]
	s_mov_b32 s4, 0xfc040000
	v_add_co_u32_e32 v152, vcc, s4, v144
	s_mov_b32 s4, 0xfc060000
	s_nop 0
	v_addc_co_u32_e32 v153, vcc, -1, v145, vcc
	s_mov_b32 s5, -1
	global_store_dwordx4 v[152:153], v[96:99], off
	global_store_dwordx4 v[150:151], v[92:95], off offset:64
	global_store_dwordx4 v[150:151], v[88:91], off offset:512
	global_store_dwordx4 v[150:151], v[84:87], off offset:576
	v_lshl_add_u64 v[150:151], v[144:145], 0, s[4:5]
	s_mov_b32 s4, 0xfc060000
	v_add_co_u32_e32 v152, vcc, s4, v144
	s_mov_b32 s4, 0xfc100000
	s_nop 0
	v_addc_co_u32_e32 v153, vcc, -1, v145, vcc
	s_mov_b32 s5, -1
	global_store_dwordx4 v[152:153], v[80:83], off
	global_store_dwordx4 v[150:151], v[76:79], off offset:64
	global_store_dwordx4 v[150:151], v[72:75], off offset:512
	global_store_dwordx4 v[150:151], v[68:71], off offset:576
	v_lshl_add_u64 v[150:151], v[144:145], 0, s[4:5]
	s_mov_b32 s4, 0xfc100000
	v_add_co_u32_e32 v152, vcc, s4, v144
	s_mov_b32 s4, 0xfc120000
	s_nop 0
	v_addc_co_u32_e32 v153, vcc, -1, v145, vcc
	s_mov_b32 s5, -1
	global_store_dwordx4 v[152:153], v[64:67], off
	global_store_dwordx4 v[150:151], v[60:63], off offset:64
	global_store_dwordx4 v[150:151], v[56:59], off offset:512
	global_store_dwordx4 v[150:151], v[52:55], off offset:576
	v_lshl_add_u64 v[150:151], v[144:145], 0, s[4:5]
	s_mov_b32 s4, 0xfc120000
	v_add_co_u32_e32 v152, vcc, s4, v144
	s_mov_b32 s4, 0xfc140000
	s_nop 0
	v_addc_co_u32_e32 v153, vcc, -1, v145, vcc
	s_mov_b32 s5, -1
	global_store_dwordx4 v[152:153], v[48:51], off
	global_store_dwordx4 v[150:151], v[44:47], off offset:64
	global_store_dwordx4 v[150:151], v[40:43], off offset:512
	global_store_dwordx4 v[150:151], v[36:39], off offset:576
	v_lshl_add_u64 v[150:151], v[144:145], 0, s[4:5]
	s_mov_b32 s4, 0xfc140000
	v_add_co_u32_e32 v152, vcc, s4, v144
	s_mov_b32 s4, 0xfc160000
	s_nop 0
	v_addc_co_u32_e32 v153, vcc, -1, v145, vcc
	s_mov_b32 s5, -1
	global_store_dwordx4 v[152:153], v[32:35], off
	global_store_dwordx4 v[150:151], v[28:31], off offset:64
	global_store_dwordx4 v[150:151], v[24:27], off offset:512
	global_store_dwordx4 v[150:151], v[20:23], off offset:576
	v_lshl_add_u64 v[150:151], v[144:145], 0, s[4:5]
	v_add_co_u32_e32 v144, vcc, 0xfc160000, v144
	s_mov_b64 s[4:5], 0
	s_nop 0
	v_addc_co_u32_e32 v145, vcc, -1, v145, vcc
	global_store_dwordx4 v[144:145], v[16:19], off
	global_store_dwordx4 v[150:151], v[12:15], off offset:64
	global_store_dwordx4 v[150:151], v[8:11], off offset:512
	global_store_dwordx4 v[150:151], v[4:7], off offset:576

; #define PG8_STAGE(bufoff, gbase, voff) do { _Pragma("unroll") for (int _i = 0; _i < 2; ++_i) \
;         __builtin_amdgcn_global_load_lds((const unsigned*)((const char*)(gbase) + (voff)[_i]), (LAS unsigned*)(lds + (bufoff) + ldsw + _i * 8192), 16, 0, 0); } while (0)
; #define PG8_LDA(dst, b, h) do { _Pragma("unroll") for (int m = 0; m < 4; ++m) _Pragma("unroll") for (int k = 0; k < 2; ++k) dst[m][k] = *(const LAS bf16x8*)(lds + PG8_SA(b, h) + aoff + m * 2048 + k * 1024); } while (0)
; #define PG8_LDB(dst, b, h) do { _Pragma("unroll") for (int n = 0; n < 2; ++n) _Pragma("unroll") for (int k = 0; k < 2; ++k) dst[n][k] = *(const LAS bf16x8*)(lds + PG8_SB(b, h) + boff + n * 2048 + k * 1024); } while (0)
; #define PG8_WAIT_V(n) asm volatile("s_waitcnt vmcnt(" #n ")" ::: "memory")
; #define PG8_WAIT_L(n) asm volatile("s_waitcnt lgkmcnt(" #n ")" ::: "memory")
; #define PG8_BAR __builtin_amdgcn_s_barrier()
; #define PG8_SCHED __builtin_amdgcn_sched_barrier(0)
; template <class Epi, class Sched, int LD>
; __device__ __forceinline__ void gemm_phase(LAS unsigned char* lds, const Gemm g, const Sched& S, const Epi& E) {
;     ...
;         for (int t = 0; t < nt; t += 2) {
;             const bool last = (t == nt - 2);
;             const char* a1 = cA + (size_t)(t + 1) * kstep;
;             const char* a2 = last ? nA : cA + (size_t)(t + 2) * kstep; const char* b2 = last ? nB : cB + (size_t)(t + 2) * kstep;
;             const char* a3 = a2 + kstep; const char* b3 = b2 + kstep;
;             PG8_LDB(B0, 0, 0); PG8_SCHED; PG8_LDA(At, 0, 0); PG8_STAGE(PG8_SA(1, 1), a1 + hstep, voffA);
;             PG8_WAIT_L(8); PG8_BAR; PG8_WAIT_L(0); PG8_MMA(0, 0, At, B0); PG8_BAR; PG8_SCHED;
;             PG8_LDB(B1, 0, 1); PG8_STAGE(PG8_SB(0, 0), b2, voffB);
;             PG8_BAR; PG8_WAIT_L(0); PG8_MMA(0, 1, At, B1); PG8_BAR;
;             PG8_LDA(At, 0, 1); PG8_STAGE(PG8_SA(0, 0), a2, voffA);
;             PG8_BAR; PG8_WAIT_L(0); PG8_MMA(1, 0, At, B0); PG8_BAR; PG8_SCHED;
;             PG8_STAGE(PG8_SB(0, 1), b2 + hstep, voffB);
;             PG8_WAIT_V(6); PG8_BAR; PG8_MMA(1, 1, At, B1); PG8_BAR;
;             PG8_LDB(B0, 1, 0); PG8_SCHED; PG8_LDA(At, 1, 0); PG8_STAGE(PG8_SA(0, 1), a2 + hstep, voffA);
;             PG8_WAIT_L(8); PG8_BAR; PG8_WAIT_L(0); PG8_MMA(0, 0, At, B0); PG8_BAR; PG8_SCHED;
.LBB0_501:
	s_add_u32 s4, s54, 0x4000
	s_addc_u32 s5, s55, 0
	s_cmp_eq_u32 s49, 28
	s_cselect_b32 s4, s50, s4
	s_cselect_b32 s5, s51, s5
	s_cselect_b32 s56, s40, s29
	s_cselect_b32 s57, s41, s47
	s_add_u32 s58, s4, 0x8000
	s_addc_u32 s59, s5, 0
	s_add_i32 s69, 0, 0x10000
	s_add_i32 m0, s52, 0xc000
	ds_read_b128 v[180:183], v146
	ds_read_b128 v[184:187], v146 offset:1024
	ds_read_b128 v[188:191], v146 offset:2048
	ds_read_b128 v[192:195], v146 offset:3072
	ds_read_b128 v[196:199], v146 offset:4096
	ds_read_b128 v[200:203], v146 offset:5120
	ds_read_b128 v[204:207], v146 offset:6144
	ds_read_b128 v[208:211], v146 offset:7168
	global_load_lds_dwordx4 v132, s[54:55]
	s_add_i32 m0, s52, 0xe000
	s_nop 0
	global_load_lds_dwordx4 v138, s[54:55]
	s_waitcnt lgkmcnt(8)
	s_barrier
	s_waitcnt lgkmcnt(0)
	s_setprio 0
	v_mfma_f32_16x16x32_bf16 v[128:131], v[148:151], v[180:183], v[128:131]
	v_mfma_f32_16x16x32_bf16 v[124:127], v[156:159], v[180:183], v[124:127]
	v_mfma_f32_16x16x32_bf16 v[120:123], v[148:151], v[188:191], v[120:123]
	v_mfma_f32_16x16x32_bf16 v[116:119], v[156:159], v[188:191], v[116:119]
	v_mfma_f32_16x16x32_bf16 v[104:107], v[148:151], v[196:199], v[104:107]
	v_mfma_f32_16x16x32_bf16 v[100:103], v[156:159], v[196:199], v[100:103]
	v_mfma_f32_16x16x32_bf16 v[88:91], v[148:151], v[204:207], v[88:91]
	v_mfma_f32_16x16x32_bf16 v[84:87], v[156:159], v[204:207], v[84:87]
	v_mfma_f32_16x16x32_bf16 v[128:131], v[152:155], v[184:187], v[128:131]
	v_mfma_f32_16x16x32_bf16 v[124:127], v[176:179], v[184:187], v[124:127]
	v_mfma_f32_16x16x32_bf16 v[120:123], v[152:155], v[192:195], v[120:123]
	v_mfma_f32_16x16x32_bf16 v[116:119], v[176:179], v[192:195], v[116:119]
	v_mfma_f32_16x16x32_bf16 v[104:107], v[152:155], v[200:203], v[104:107]
	v_mfma_f32_16x16x32_bf16 v[100:103], v[176:179], v[200:203], v[100:103]
	s_barrier
	s_setprio 3
	v_mfma_f32_16x16x32_bf16 v[88:91], v[152:155], v[208:211], v[88:91]
	v_mfma_f32_16x16x32_bf16 v[84:87], v[176:179], v[208:211], v[84:87]
	s_setprio 2
	s_add_i32 s72, 0, 0x14000
	s_add_i32 s69, s69, s39
	ds_read_b128 v[212:215], v228 offset:16384
	ds_read_b128 v[216:219], v228 offset:17408
	ds_read_b128 v[220:223], v228 offset:18432
	ds_read_b128 v[224:227], v228 offset:19456
	s_mov_b32 m0, s69
	s_nop 0
	global_load_lds_dwordx4 v132, s[56:57]
	s_add_i32 m0, s69, 0x2000
	s_nop 0
	global_load_lds_dwordx4 v138, s[56:57]
	s_barrier
	s_waitcnt lgkmcnt(0)
	s_setprio 0
	v_mfma_f32_16x16x32_bf16 v[112:115], v[212:215], v[180:183], v[112:115]
	v_mfma_f32_16x16x32_bf16 v[108:111], v[220:223], v[180:183], v[108:111]
	v_mfma_f32_16x16x32_bf16 v[96:99], v[212:215], v[188:191], v[96:99]
	v_mfma_f32_16x16x32_bf16 v[92:95], v[220:223], v[188:191], v[92:95]
	v_mfma_f32_16x16x32_bf16 v[80:83], v[212:215], v[196:199], v[80:83]
	v_mfma_f32_16x16x32_bf16 v[76:79], v[220:223], v[196:199], v[76:79]
	v_mfma_f32_16x16x32_bf16 v[72:75], v[212:215], v[204:207], v[72:75]
	v_mfma_f32_16x16x32_bf16 v[68:71], v[220:223], v[204:207], v[68:71]
	v_mfma_f32_16x16x32_bf16 v[112:115], v[216:219], v[184:187], v[112:115]
	v_mfma_f32_16x16x32_bf16 v[108:111], v[224:227], v[184:187], v[108:111]
	v_mfma_f32_16x16x32_bf16 v[96:99], v[216:219], v[192:195], v[96:99]
	v_mfma_f32_16x16x32_bf16 v[92:95], v[224:227], v[192:195], v[92:95]
	v_mfma_f32_16x16x32_bf16 v[80:83], v[216:219], v[200:203], v[80:83]
	v_mfma_f32_16x16x32_bf16 v[76:79], v[224:227], v[200:203], v[76:79]
	s_barrier
	s_setprio 3
	v_mfma_f32_16x16x32_bf16 v[72:75], v[216:219], v[208:211], v[72:75]
	v_mfma_f32_16x16x32_bf16 v[68:71], v[224:227], v[208:211], v[68:71]
	s_setprio 2
	s_mov_b32 m0, s52
	ds_read_b128 v[180:183], v146 offset:16384
	ds_read_b128 v[184:187], v146 offset:17408
	ds_read_b128 v[188:191], v146 offset:18432
	ds_read_b128 v[192:195], v146 offset:19456
	ds_read_b128 v[196:199], v146 offset:20480
	ds_read_b128 v[200:203], v146 offset:21504
	ds_read_b128 v[204:207], v146 offset:22528
	ds_read_b128 v[208:211], v146 offset:23552
	global_load_lds_dwordx4 v132, s[4:5]
	s_mov_b32 m0, s53
	s_nop 0
	global_load_lds_dwordx4 v138, s[4:5]
	s_waitcnt vmcnt(10)
	s_barrier
	s_waitcnt lgkmcnt(0)
	s_setprio 0
	v_mfma_f32_16x16x32_bf16 v[64:67], v[148:151], v[180:183], v[64:67]
	v_mfma_f32_16x16x32_bf16 v[60:63], v[156:159], v[180:183], v[60:63]
	v_mfma_f32_16x16x32_bf16 v[56:59], v[148:151], v[188:191], v[56:59]
	v_mfma_f32_16x16x32_bf16 v[52:55], v[156:159], v[188:191], v[52:55]
	v_mfma_f32_16x16x32_bf16 v[40:43], v[148:151], v[196:199], v[40:43]
	v_mfma_f32_16x16x32_bf16 v[36:39], v[156:159], v[196:199], v[36:39]
	v_mfma_f32_16x16x32_bf16 v[24:27], v[148:151], v[204:207], v[24:27]
	v_mfma_f32_16x16x32_bf16 v[20:23], v[156:159], v[204:207], v[20:23]
	v_mfma_f32_16x16x32_bf16 v[64:67], v[152:155], v[184:187], v[64:67]
	v_mfma_f32_16x16x32_bf16 v[60:63], v[176:179], v[184:187], v[60:63]
	v_mfma_f32_16x16x32_bf16 v[56:59], v[152:155], v[192:195], v[56:59]
	v_mfma_f32_16x16x32_bf16 v[52:55], v[176:179], v[192:195], v[52:55]
	v_mfma_f32_16x16x32_bf16 v[40:43], v[152:155], v[200:203], v[40:43]
	v_mfma_f32_16x16x32_bf16 v[36:39], v[176:179], v[200:203], v[36:39]
	s_barrier
	s_setprio 3
	v_mfma_f32_16x16x32_bf16 v[24:27], v[152:155], v[208:211], v[24:27]
	v_mfma_f32_16x16x32_bf16 v[20:23], v[176:179], v[208:211], v[20:23]
	s_setprio 2
	ds_read_b128 v[148:151], v228 offset:32768
	ds_read_b128 v[152:155], v228 offset:33792
	ds_read_b128 v[156:159], v228 offset:34816
	ds_read_b128 v[176:179], v228 offset:35840
	s_add_u32 s70, s56, 0x4000
	s_addc_u32 s71, s57, 0
	s_add_i32 s69, s72, s39
	s_mov_b32 m0, s69
	s_nop 0
	global_load_lds_dwordx4 v132, s[70:71]
	s_add_i32 m0, s69, 0x2000
	s_nop 0
	global_load_lds_dwordx4 v138, s[70:71]
	s_waitcnt vmcnt(6)
	s_barrier
; #define PG8_STAGE(bufoff, gbase, voff) do { _Pragma("unroll") for (int _i = 0; _i < 2; ++_i) \
;         __builtin_amdgcn_global_load_lds((const unsigned*)((const char*)(gbase) + (voff)[_i]), (LAS unsigned*)(lds + (bufoff) + ldsw + _i * 8192), 16, 0, 0); } while (0)
; #define PG8_LDA(dst, b, h) do { _Pragma("unroll") for (int m = 0; m < 4; ++m) _Pragma("unroll") for (int k = 0; k < 2; ++k) dst[m][k] = *(const LAS bf16x8*)(lds + PG8_SA(b, h) + aoff + m * 2048 + k * 1024); } while (0)
; #define PG8_LDB(dst, b, h) do { _Pragma("unroll") for (int n = 0; n < 2; ++n) _Pragma("unroll") for (int k = 0; k < 2; ++k) dst[n][k] = *(const LAS bf16x8*)(lds + PG8_SB(b, h) + boff + n * 2048 + k * 1024); } while (0)
; #define PG8_MMA(ai, bj, At, Bt) do { __builtin_amdgcn_s_setprio(1); _Pragma("unroll") for (int m = 0; m < 4; ++m) _Pragma("unroll") for (int n = 0; n < 2; ++n) _Pragma("unroll") for (int k = 0; k < 2; ++k) \
;         acc[ai][bj][m][n] = __builtin_amdgcn_mfma_f32_16x16x32_bf16(Bt[n][k], At[m][k], acc[ai][bj][m][n], 0, 0, 0); __builtin_amdgcn_s_setprio(0); } while (0)
; #define PG8_WAIT_V(n) asm volatile("s_waitcnt vmcnt(" #n ")" ::: "memory")
; #define PG8_WAIT_L(n) asm volatile("s_waitcnt lgkmcnt(" #n ")" ::: "memory")
; #define PG8_BAR __builtin_amdgcn_s_barrier()
; #define PG8_SCHED __builtin_amdgcn_sched_barrier(0)
; template <class Epi, class Sched, int LD>
; __device__ __forceinline__ void gemm_phase(LAS unsigned char* lds, const Gemm g, const Sched& S, const Epi& E) {
;     ...
;             PG8_BAR; PG8_WAIT_L(0); PG8_MMA(1, 0, At, B0); PG8_BAR; PG8_SCHED;
;             PG8_STAGE(PG8_SB(0, 1), b2 + hstep, voffB);
;             PG8_WAIT_V(6); PG8_BAR; PG8_MMA(1, 1, At, B1); PG8_BAR;
;             PG8_LDB(B0, 1, 0); PG8_SCHED; PG8_LDA(At, 1, 0); PG8_STAGE(PG8_SA(0, 1), a2 + hstep, voffA);
;             PG8_WAIT_L(8); PG8_BAR; PG8_WAIT_L(0); PG8_MMA(0, 0, At, B0); PG8_BAR; PG8_SCHED;
;             PG8_LDB(B1, 1, 1); PG8_STAGE(PG8_SB(1, 0), b3, voffB);
;             PG8_BAR; PG8_WAIT_L(0); PG8_MMA(0, 1, At, B1); PG8_BAR;
	s_setprio 0
	v_mfma_f32_16x16x32_bf16 v[48:51], v[212:215], v[180:183], v[48:51]
	v_mfma_f32_16x16x32_bf16 v[44:47], v[220:223], v[180:183], v[44:47]
	v_mfma_f32_16x16x32_bf16 v[32:35], v[212:215], v[188:191], v[32:35]
	v_mfma_f32_16x16x32_bf16 v[28:31], v[220:223], v[188:191], v[28:31]
	v_mfma_f32_16x16x32_bf16 v[16:19], v[212:215], v[196:199], v[16:19]
	v_mfma_f32_16x16x32_bf16 v[12:15], v[220:223], v[196:199], v[12:15]
	v_mfma_f32_16x16x32_bf16 v[8:11], v[212:215], v[204:207], v[8:11]
	v_mfma_f32_16x16x32_bf16 v[4:7], v[220:223], v[204:207], v[4:7]
	v_mfma_f32_16x16x32_bf16 v[48:51], v[216:219], v[184:187], v[48:51]
	v_mfma_f32_16x16x32_bf16 v[44:47], v[224:227], v[184:187], v[44:47]
	v_mfma_f32_16x16x32_bf16 v[32:35], v[216:219], v[192:195], v[32:35]
	v_mfma_f32_16x16x32_bf16 v[28:31], v[224:227], v[192:195], v[28:31]
	v_mfma_f32_16x16x32_bf16 v[16:19], v[216:219], v[200:203], v[16:19]
	v_mfma_f32_16x16x32_bf16 v[12:15], v[224:227], v[200:203], v[12:15]
	s_barrier
	s_setprio 3
	v_mfma_f32_16x16x32_bf16 v[8:11], v[216:219], v[208:211], v[8:11]
	v_mfma_f32_16x16x32_bf16 v[4:7], v[224:227], v[208:211], v[4:7]
	s_setprio 2
	s_add_i32 s69, 0, 0x18000
	s_add_u32 s4, s4, 0x4000
	s_addc_u32 s5, s5, 0
	s_mov_b32 m0, s60
	ds_read_b128 v[180:183], v146 offset:32768
	ds_read_b128 v[184:187], v146 offset:33792
	ds_read_b128 v[188:191], v146 offset:34816
	ds_read_b128 v[192:195], v146 offset:35840
	ds_read_b128 v[196:199], v146 offset:36864
	ds_read_b128 v[200:203], v146 offset:37888
	ds_read_b128 v[204:207], v146 offset:38912
	ds_read_b128 v[208:211], v146 offset:39936
	global_load_lds_dwordx4 v132, s[4:5]
	s_mov_b32 m0, s61
	s_nop 0
	global_load_lds_dwordx4 v138, s[4:5]
	s_waitcnt lgkmcnt(8)
	s_barrier
	s_waitcnt lgkmcnt(0)
	s_setprio 0
	v_mfma_f32_16x16x32_bf16 v[128:131], v[148:151], v[180:183], v[128:131]
	v_mfma_f32_16x16x32_bf16 v[124:127], v[156:159], v[180:183], v[124:127]
	v_mfma_f32_16x16x32_bf16 v[120:123], v[148:151], v[188:191], v[120:123]
	v_mfma_f32_16x16x32_bf16 v[116:119], v[156:159], v[188:191], v[116:119]
	v_mfma_f32_16x16x32_bf16 v[104:107], v[148:151], v[196:199], v[104:107]
	v_mfma_f32_16x16x32_bf16 v[100:103], v[156:159], v[196:199], v[100:103]
	v_mfma_f32_16x16x32_bf16 v[88:91], v[148:151], v[204:207], v[88:91]
	v_mfma_f32_16x16x32_bf16 v[84:87], v[156:159], v[204:207], v[84:87]
	v_mfma_f32_16x16x32_bf16 v[128:131], v[152:155], v[184:187], v[128:131]
	v_mfma_f32_16x16x32_bf16 v[124:127], v[176:179], v[184:187], v[124:127]
	v_mfma_f32_16x16x32_bf16 v[120:123], v[152:155], v[192:195], v[120:123]
	v_mfma_f32_16x16x32_bf16 v[116:119], v[176:179], v[192:195], v[116:119]
	v_mfma_f32_16x16x32_bf16 v[104:107], v[152:155], v[200:203], v[104:107]
	v_mfma_f32_16x16x32_bf16 v[100:103], v[176:179], v[200:203], v[100:103]
	s_barrier
	s_setprio 3
	v_mfma_f32_16x16x32_bf16 v[88:91], v[152:155], v[208:211], v[88:91]
	v_mfma_f32_16x16x32_bf16 v[84:87], v[176:179], v[208:211], v[84:87]
	s_setprio 2
	s_add_i32 s70, 0, 0x1c000
	s_add_u32 s4, s56, 0x8000
	s_addc_u32 s5, s57, 0
	s_add_i32 s69, s69, s39
	ds_read_b128 v[212:215], v228 offset:49152
	ds_read_b128 v[216:219], v228 offset:50176
	ds_read_b128 v[220:223], v228 offset:51200
	ds_read_b128 v[224:227], v228 offset:52224
	s_mov_b32 m0, s69
	s_nop 0
	global_load_lds_dwordx4 v132, s[4:5]
	s_add_i32 m0, s69, 0x2000
	s_nop 0
	global_load_lds_dwordx4 v138, s[4:5]
	s_barrier
	s_waitcnt lgkmcnt(0)
	s_setprio 0
	v_mfma_f32_16x16x32_bf16 v[112:115], v[212:215], v[180:183], v[112:115]
	v_mfma_f32_16x16x32_bf16 v[108:111], v[220:223], v[180:183], v[108:111]
	v_mfma_f32_16x16x32_bf16 v[96:99], v[212:215], v[188:191], v[96:99]
	v_mfma_f32_16x16x32_bf16 v[92:95], v[220:223], v[188:191], v[92:95]
	v_mfma_f32_16x16x32_bf16 v[80:83], v[212:215], v[196:199], v[80:83]
	v_mfma_f32_16x16x32_bf16 v[76:79], v[220:223], v[196:199], v[76:79]
	v_mfma_f32_16x16x32_bf16 v[72:75], v[212:215], v[204:207], v[72:75]
	v_mfma_f32_16x16x32_bf16 v[68:71], v[220:223], v[204:207], v[68:71]
	v_mfma_f32_16x16x32_bf16 v[112:115], v[216:219], v[184:187], v[112:115]
	v_mfma_f32_16x16x32_bf16 v[108:111], v[224:227], v[184:187], v[108:111]
	v_mfma_f32_16x16x32_bf16 v[96:99], v[216:219], v[192:195], v[96:99]
	v_mfma_f32_16x16x32_bf16 v[92:95], v[224:227], v[192:195], v[92:95]
	v_mfma_f32_16x16x32_bf16 v[80:83], v[216:219], v[200:203], v[80:83]
	v_mfma_f32_16x16x32_bf16 v[76:79], v[224:227], v[200:203], v[76:79]
	s_barrier
	s_setprio 3
	v_mfma_f32_16x16x32_bf16 v[72:75], v[216:219], v[208:211], v[72:75]
	v_mfma_f32_16x16x32_bf16 v[68:71], v[224:227], v[208:211], v[68:71]
	s_setprio 2
	s_mov_b32 m0, s64
	ds_read_b128 v[180:183], v146 offset:49152
	ds_read_b128 v[184:187], v146 offset:50176
	ds_read_b128 v[188:191], v146 offset:51200
	ds_read_b128 v[192:195], v146 offset:52224
	ds_read_b128 v[196:199], v146 offset:53248
	ds_read_b128 v[200:203], v146 offset:54272
	ds_read_b128 v[204:207], v146 offset:55296
	ds_read_b128 v[208:211], v146 offset:56320
	global_load_lds_dwordx4 v132, s[58:59]
	s_mov_b32 m0, s65
	s_nop 0
	global_load_lds_dwordx4 v138, s[58:59]
	s_waitcnt vmcnt(10)
	s_barrier
; #define PG8_STAGE(bufoff, gbase, voff) do { _Pragma("unroll") for (int _i = 0; _i < 2; ++_i) \
;         __builtin_amdgcn_global_load_lds((const unsigned*)((const char*)(gbase) + (voff)[_i]), (LAS unsigned*)(lds + (bufoff) + ldsw + _i * 8192), 16, 0, 0); } while (0)
; #define PG8_LDA(dst, b, h) do { _Pragma("unroll") for (int m = 0; m < 4; ++m) _Pragma("unroll") for (int k = 0; k < 2; ++k) dst[m][k] = *(const LAS bf16x8*)(lds + PG8_SA(b, h) + aoff + m * 2048 + k * 1024); } while (0)
; #define PG8_MMA(ai, bj, At, Bt) do { __builtin_amdgcn_s_setprio(1); _Pragma("unroll") for (int m = 0; m < 4; ++m) _Pragma("unroll") for (int n = 0; n < 2; ++n) _Pragma("unroll") for (int k = 0; k < 2; ++k) \
;         acc[ai][bj][m][n] = __builtin_amdgcn_mfma_f32_16x16x32_bf16(Bt[n][k], At[m][k], acc[ai][bj][m][n], 0, 0, 0); __builtin_amdgcn_s_setprio(0); } while (0)
; #define PG8_WAIT_V(n) asm volatile("s_waitcnt vmcnt(" #n ")" ::: "memory")
; #define PG8_WAIT_L(n) asm volatile("s_waitcnt lgkmcnt(" #n ")" ::: "memory")
; #define PG8_BAR __builtin_amdgcn_s_barrier()
; #define PG8_SCHED __builtin_amdgcn_sched_barrier(0)
;     __device__ __forceinline__ void operator()(const f32x4 (&acc)[2][2][4][2], const Unit& u, int wr, int wc, int fr, int fq) const {
;     ...
;         } else if (wc == 0) {
; #pragma unroll
;             for (int ai = 0; ai < 2; ++ai)
; #pragma unroll
;                 for (int m = 0; m < 4; ++m) {
;                     float* rowp = DT + (size_t)(row0 + ai * HALF + m * 16) * 32 + 8 * fq;
;                     *(f32x4*)rowp = acc[ai][0][m][0]; *(f32x4*)(rowp + 4) = acc[ai][0][m][1];
;                 }
; template <class Epi, class Sched, int LD>
; __device__ __forceinline__ void gemm_phase(LAS unsigned char* lds, const Gemm g, const Sched& S, const Epi& E) {
;     ...
;             PG8_BAR; PG8_WAIT_L(0); PG8_MMA(0, 1, At, B1); PG8_BAR;
;             PG8_LDA(At, 1, 1); PG8_STAGE(PG8_SA(1, 0), a3, voffA);
;             PG8_BAR; PG8_WAIT_L(0); PG8_MMA(1, 0, At, B0); PG8_BAR; PG8_SCHED;
;             PG8_STAGE(PG8_SB(1, 1), b3 + hstep, voffB);
;             PG8_WAIT_V(6); PG8_BAR; PG8_MMA(1, 1, At, B1); PG8_BAR;
	s_waitcnt lgkmcnt(0)
	s_setprio 0
	v_mfma_f32_16x16x32_bf16 v[64:67], v[148:151], v[180:183], v[64:67]
	v_mfma_f32_16x16x32_bf16 v[60:63], v[156:159], v[180:183], v[60:63]
	v_mfma_f32_16x16x32_bf16 v[56:59], v[148:151], v[188:191], v[56:59]
	v_mfma_f32_16x16x32_bf16 v[52:55], v[156:159], v[188:191], v[52:55]
	v_mfma_f32_16x16x32_bf16 v[40:43], v[148:151], v[196:199], v[40:43]
	v_mfma_f32_16x16x32_bf16 v[36:39], v[156:159], v[196:199], v[36:39]
	v_mfma_f32_16x16x32_bf16 v[24:27], v[148:151], v[204:207], v[24:27]
	v_mfma_f32_16x16x32_bf16 v[20:23], v[156:159], v[204:207], v[20:23]
	v_mfma_f32_16x16x32_bf16 v[64:67], v[152:155], v[184:187], v[64:67]
	v_mfma_f32_16x16x32_bf16 v[60:63], v[176:179], v[184:187], v[60:63]
	v_mfma_f32_16x16x32_bf16 v[56:59], v[152:155], v[192:195], v[56:59]
	v_mfma_f32_16x16x32_bf16 v[52:55], v[176:179], v[192:195], v[52:55]
	v_mfma_f32_16x16x32_bf16 v[40:43], v[152:155], v[200:203], v[40:43]
	v_mfma_f32_16x16x32_bf16 v[36:39], v[176:179], v[200:203], v[36:39]
	s_barrier
	s_setprio 3
	v_mfma_f32_16x16x32_bf16 v[24:27], v[152:155], v[208:211], v[24:27]
	v_mfma_f32_16x16x32_bf16 v[20:23], v[176:179], v[208:211], v[20:23]
	s_setprio 2
	ds_read_b128 v[148:151], v228
	ds_read_b128 v[152:155], v228 offset:1024
	ds_read_b128 v[156:159], v228 offset:2048
	ds_read_b128 v[176:179], v228 offset:3072
	s_add_u32 s4, s56, 0xc000
	s_addc_u32 s5, s57, 0
	s_add_i32 s56, s70, s39
	s_mov_b32 m0, s56
	s_nop 0
	global_load_lds_dwordx4 v132, s[4:5]
	s_add_i32 m0, s56, 0x2000
	s_nop 0
	global_load_lds_dwordx4 v138, s[4:5]
	s_waitcnt vmcnt(6)
	s_barrier
	s_setprio 0
	v_mfma_f32_16x16x32_bf16 v[48:51], v[212:215], v[180:183], v[48:51]
	v_mfma_f32_16x16x32_bf16 v[44:47], v[220:223], v[180:183], v[44:47]
	v_mfma_f32_16x16x32_bf16 v[32:35], v[212:215], v[188:191], v[32:35]
	v_mfma_f32_16x16x32_bf16 v[28:31], v[220:223], v[188:191], v[28:31]
	v_mfma_f32_16x16x32_bf16 v[16:19], v[212:215], v[196:199], v[16:19]
	v_mfma_f32_16x16x32_bf16 v[12:15], v[220:223], v[196:199], v[12:15]
	v_mfma_f32_16x16x32_bf16 v[8:11], v[212:215], v[204:207], v[8:11]
	v_mfma_f32_16x16x32_bf16 v[4:7], v[220:223], v[204:207], v[4:7]
	v_mfma_f32_16x16x32_bf16 v[48:51], v[216:219], v[184:187], v[48:51]
	v_mfma_f32_16x16x32_bf16 v[44:47], v[224:227], v[184:187], v[44:47]
	v_mfma_f32_16x16x32_bf16 v[32:35], v[216:219], v[192:195], v[32:35]
	v_mfma_f32_16x16x32_bf16 v[28:31], v[224:227], v[192:195], v[28:31]
	v_mfma_f32_16x16x32_bf16 v[16:19], v[216:219], v[200:203], v[16:19]
	v_mfma_f32_16x16x32_bf16 v[12:15], v[224:227], v[200:203], v[12:15]
	s_barrier
	s_setprio 3
	v_mfma_f32_16x16x32_bf16 v[8:11], v[216:219], v[208:211], v[8:11]
	v_mfma_f32_16x16x32_bf16 v[4:7], v[224:227], v[208:211], v[4:7]
	s_setprio 2
	s_add_i32 s49, s49, 2
	s_add_u32 s54, s54, 0x10000
	s_addc_u32 s55, s55, 0
	s_add_u32 s29, s29, 0x10000
	s_addc_u32 s47, s47, 0
	s_cmp_gt_u32 s49, 29
	s_cbranch_scc0 .LBB0_501
	s_setprio 0
	v_lshl_add_u32 v142, s68, 8, v137
	s_cmp_gt_i32 s67, 35
	s_mov_b64 s[4:5], -1
	s_cbranch_scc0 .LBB0_506
	s_andn2_b64 vcc, exec, s[42:43]
	s_cbranch_vccnz .LBB0_505
	v_or_b32_e32 v150, 16, v142
	v_ashrrev_i32_e32 v143, 31, v142
	v_ashrrev_i32_e32 v151, 31, v150
	v_lshlrev_b64 v[148:149], 7, v[142:143]
	v_lshlrev_b64 v[150:151], 7, v[150:151]
	v_lshl_add_u64 v[148:149], v[140:141], 0, v[148:149]
	v_lshl_add_u64 v[150:151], v[140:141], 0, v[150:151]
	global_store_dwordx4 v[148:149], v[128:131], off
	global_store_dwordx4 v[148:149], v[124:127], off offset:16
	global_store_dwordx4 v[150:151], v[120:123], off
	global_store_dwordx4 v[150:151], v[116:119], off offset:16
	v_or_b32_e32 v150, 32, v142
	v_ashrrev_i32_e32 v151, 31, v150
	v_lshlrev_b64 v[150:151], 7, v[150:151]
	v_lshl_add_u64 v[150:151], v[140:141], 0, v[150:151]
	global_store_dwordx4 v[150:151], v[104:107], off
	global_store_dwordx4 v[150:151], v[100:103], off offset:16
	v_or_b32_e32 v150, 48, v142
	v_ashrrev_i32_e32 v151, 31, v150
	v_lshlrev_b64 v[150:151], 7, v[150:151]
	v_lshl_add_u64 v[150:151], v[140:141], 0, v[150:151]
	s_mov_b64 s[4:5], 0x4000
	global_store_dwordx4 v[150:151], v[88:91], off
	global_store_dwordx4 v[150:151], v[84:87], off offset:16
	v_lshl_add_u64 v[150:151], v[148:149], 0, s[4:5]
	s_movk_i32 s4, 0x4000
	v_add_co_u32_e32 v152, vcc, s4, v148
	s_mov_b64 s[4:5], 0x4800
	s_nop 0
	v_addc_co_u32_e32 v153, vcc, 0, v149, vcc
	global_store_dwordx4 v[152:153], v[64:67], off
	global_store_dwordx4 v[150:151], v[60:63], off offset:16
	v_lshl_add_u64 v[150:151], v[148:149], 0, s[4:5]
	global_store_dwordx4 v[152:153], v[56:59], off offset:2048
	global_store_dwordx4 v[150:151], v[52:55], off offset:16
	s_mov_b64 s[4:5], 0x5000
	v_add_co_u32_e32 v152, vcc, 0x5000, v148
	v_lshl_add_u64 v[150:151], v[148:149], 0, s[4:5]
	s_nop 0
	v_addc_co_u32_e32 v153, vcc, 0, v149, vcc
	s_mov_b64 s[4:5], 0x5800
	global_store_dwordx4 v[152:153], v[40:43], off
	global_store_dwordx4 v[150:151], v[36:39], off offset:16
	v_lshl_add_u64 v[148:149], v[148:149], 0, s[4:5]
	global_store_dwordx4 v[152:153], v[24:27], off offset:2048
	global_store_dwordx4 v[148:149], v[20:23], off offset:16

; #define PG8_STAGE(bufoff, gbase, voff) do { _Pragma("unroll") for (int _i = 0; _i < 2; ++_i) \
;         __builtin_amdgcn_global_load_lds((const unsigned*)((const char*)(gbase) + (voff)[_i]), (LAS unsigned*)(lds + (bufoff) + ldsw + _i * 8192), 16, 0, 0); } while (0)
; #define PG8_LDA(dst, b, h) do { _Pragma("unroll") for (int m = 0; m < 4; ++m) _Pragma("unroll") for (int k = 0; k < 2; ++k) dst[m][k] = *(const LAS bf16x8*)(lds + PG8_SA(b, h) + aoff + m * 2048 + k * 1024); } while (0)
; #define PG8_LDB(dst, b, h) do { _Pragma("unroll") for (int n = 0; n < 2; ++n) _Pragma("unroll") for (int k = 0; k < 2; ++k) dst[n][k] = *(const LAS bf16x8*)(lds + PG8_SB(b, h) + boff + n * 2048 + k * 1024); } while (0)
; #define PG8_MMA(ai, bj, At, Bt) do { __builtin_amdgcn_s_setprio(1); _Pragma("unroll") for (int m = 0; m < 4; ++m) _Pragma("unroll") for (int n = 0; n < 2; ++n) _Pragma("unroll") for (int k = 0; k < 2; ++k) \
;         acc[ai][bj][m][n] = __builtin_amdgcn_mfma_f32_16x16x32_bf16(Bt[n][k], At[m][k], acc[ai][bj][m][n], 0, 0, 0); __builtin_amdgcn_s_setprio(0); } while (0)
; #define PG8_WAIT_V(n) asm volatile("s_waitcnt vmcnt(" #n ")" ::: "memory")
; #define PG8_WAIT_L(n) asm volatile("s_waitcnt lgkmcnt(" #n ")" ::: "memory")
; #define PG8_BAR __builtin_amdgcn_s_barrier()
; #define PG8_SCHED __builtin_amdgcn_sched_barrier(0)
; template <class Epi, class Sched, int LD>
; __device__ __forceinline__ void gemm_phase(LAS unsigned char* lds, const Gemm g, const Sched& S, const Epi& E) {
;     ...
;             PG8_LDB(B0, 0, 0); PG8_SCHED; PG8_LDA(At, 0, 0); PG8_STAGE(PG8_SA(1, 1), a1 + hstep, voffA);
;             PG8_WAIT_L(8); PG8_BAR; PG8_WAIT_L(0); PG8_MMA(0, 0, At, B0); PG8_BAR; PG8_SCHED;
;             PG8_LDB(B1, 0, 1); PG8_STAGE(PG8_SB(0, 0), b2, voffB);
;             PG8_BAR; PG8_WAIT_L(0); PG8_MMA(0, 1, At, B1); PG8_BAR;
;             PG8_LDA(At, 0, 1); PG8_STAGE(PG8_SA(0, 0), a2, voffA);
;             PG8_BAR; PG8_WAIT_L(0); PG8_MMA(1, 0, At, B0); PG8_BAR; PG8_SCHED;
;             PG8_STAGE(PG8_SB(0, 1), b2 + hstep, voffB);
;             PG8_WAIT_V(6); PG8_BAR; PG8_MMA(1, 1, At, B1); PG8_BAR;
.LBB0_899:
	s_add_u32 s4, s50, 0x4000
	s_addc_u32 s5, s51, 0
	s_cmp_eq_u32 s70, 28
	s_cselect_b32 s4, s48, s4
	s_cselect_b32 s5, s49, s5
	s_cselect_b32 s54, s40, s45
	s_cselect_b32 s55, s41, s47
	s_add_u32 s56, s4, 0x8000
	s_addc_u32 s57, s5, 0
	s_add_i32 s71, 0, 0x10000
	s_add_i32 m0, s29, 0xc000
	ds_read_b128 v[180:183], v144
	ds_read_b128 v[184:187], v144 offset:1024
	ds_read_b128 v[188:191], v144 offset:2048
	ds_read_b128 v[192:195], v144 offset:3072
	ds_read_b128 v[196:199], v144 offset:4096
	ds_read_b128 v[200:203], v144 offset:5120
	ds_read_b128 v[204:207], v144 offset:6144
	ds_read_b128 v[208:211], v144 offset:7168
	global_load_lds_dwordx4 v138, s[50:51]
	s_add_i32 m0, s29, 0xe000
	s_nop 0
	global_load_lds_dwordx4 v140, s[50:51]
	s_waitcnt lgkmcnt(8)
	s_barrier
	s_waitcnt lgkmcnt(0)
	s_setprio 0
	v_mfma_f32_16x16x32_bf16 v[128:131], v[146:149], v[180:183], v[128:131]
	v_mfma_f32_16x16x32_bf16 v[120:123], v[154:157], v[180:183], v[120:123]
	v_mfma_f32_16x16x32_bf16 v[112:115], v[146:149], v[188:191], v[112:115]
	v_mfma_f32_16x16x32_bf16 v[104:107], v[154:157], v[188:191], v[104:107]
	v_mfma_f32_16x16x32_bf16 v[96:99], v[146:149], v[196:199], v[96:99]
	v_mfma_f32_16x16x32_bf16 v[88:91], v[154:157], v[196:199], v[88:91]
	v_mfma_f32_16x16x32_bf16 v[80:83], v[146:149], v[204:207], v[80:83]
	v_mfma_f32_16x16x32_bf16 v[72:75], v[154:157], v[204:207], v[72:75]
	v_mfma_f32_16x16x32_bf16 v[128:131], v[150:153], v[184:187], v[128:131]
	v_mfma_f32_16x16x32_bf16 v[120:123], v[176:179], v[184:187], v[120:123]
	v_mfma_f32_16x16x32_bf16 v[112:115], v[150:153], v[192:195], v[112:115]
	v_mfma_f32_16x16x32_bf16 v[104:107], v[176:179], v[192:195], v[104:107]
	v_mfma_f32_16x16x32_bf16 v[96:99], v[150:153], v[200:203], v[96:99]
	v_mfma_f32_16x16x32_bf16 v[88:91], v[176:179], v[200:203], v[88:91]
	s_barrier
	s_setprio 3
	v_mfma_f32_16x16x32_bf16 v[80:83], v[150:153], v[208:211], v[80:83]
	v_mfma_f32_16x16x32_bf16 v[72:75], v[176:179], v[208:211], v[72:75]
	s_setprio 2
	s_add_i32 s74, 0, 0x14000
	s_add_i32 s71, s71, s28
	s_mov_b32 m0, s71
	ds_read_b128 v[212:215], v228 offset:16384
	ds_read_b128 v[216:219], v228 offset:17408
	ds_read_b128 v[220:223], v228 offset:18432
	ds_read_b128 v[224:227], v228 offset:19456
	global_load_lds_dwordx4 v138, s[54:55]
	s_add_i32 m0, s71, 0x2000
	s_nop 0
	global_load_lds_dwordx4 v140, s[54:55]
	s_barrier
	s_waitcnt lgkmcnt(0)
	s_setprio 0
	v_mfma_f32_16x16x32_bf16 v[124:127], v[212:215], v[180:183], v[124:127]
	v_mfma_f32_16x16x32_bf16 v[116:119], v[220:223], v[180:183], v[116:119]
	v_mfma_f32_16x16x32_bf16 v[108:111], v[212:215], v[188:191], v[108:111]
	v_mfma_f32_16x16x32_bf16 v[100:103], v[220:223], v[188:191], v[100:103]
	v_mfma_f32_16x16x32_bf16 v[92:95], v[212:215], v[196:199], v[92:95]
	v_mfma_f32_16x16x32_bf16 v[84:87], v[220:223], v[196:199], v[84:87]
	v_mfma_f32_16x16x32_bf16 v[76:79], v[212:215], v[204:207], v[76:79]
	v_mfma_f32_16x16x32_bf16 v[68:71], v[220:223], v[204:207], v[68:71]
	v_mfma_f32_16x16x32_bf16 v[124:127], v[216:219], v[184:187], v[124:127]
	v_mfma_f32_16x16x32_bf16 v[116:119], v[224:227], v[184:187], v[116:119]
	v_mfma_f32_16x16x32_bf16 v[108:111], v[216:219], v[192:195], v[108:111]
	v_mfma_f32_16x16x32_bf16 v[100:103], v[224:227], v[192:195], v[100:103]
	v_mfma_f32_16x16x32_bf16 v[92:95], v[216:219], v[200:203], v[92:95]
	v_mfma_f32_16x16x32_bf16 v[84:87], v[224:227], v[200:203], v[84:87]
	s_barrier
	s_setprio 3
	v_mfma_f32_16x16x32_bf16 v[76:79], v[216:219], v[208:211], v[76:79]
	v_mfma_f32_16x16x32_bf16 v[68:71], v[224:227], v[208:211], v[68:71]
	s_setprio 2
	s_mov_b32 m0, s29
	ds_read_b128 v[180:183], v144 offset:16384
	ds_read_b128 v[184:187], v144 offset:17408
	ds_read_b128 v[188:191], v144 offset:18432
	ds_read_b128 v[192:195], v144 offset:19456
	ds_read_b128 v[196:199], v144 offset:20480
	ds_read_b128 v[200:203], v144 offset:21504
	ds_read_b128 v[204:207], v144 offset:22528
	ds_read_b128 v[208:211], v144 offset:23552
	global_load_lds_dwordx4 v138, s[4:5]
	s_mov_b32 m0, s39
	s_nop 0
	global_load_lds_dwordx4 v140, s[4:5]
	s_waitcnt vmcnt(10)
	s_barrier
	s_waitcnt lgkmcnt(0)
	s_setprio 0
	v_mfma_f32_16x16x32_bf16 v[64:67], v[146:149], v[180:183], v[64:67]
	v_mfma_f32_16x16x32_bf16 v[56:59], v[154:157], v[180:183], v[56:59]
	v_mfma_f32_16x16x32_bf16 v[48:51], v[146:149], v[188:191], v[48:51]
	v_mfma_f32_16x16x32_bf16 v[40:43], v[154:157], v[188:191], v[40:43]
	v_mfma_f32_16x16x32_bf16 v[32:35], v[146:149], v[196:199], v[32:35]
	v_mfma_f32_16x16x32_bf16 v[24:27], v[154:157], v[196:199], v[24:27]
	v_mfma_f32_16x16x32_bf16 v[16:19], v[146:149], v[204:207], v[16:19]
	v_mfma_f32_16x16x32_bf16 v[8:11], v[154:157], v[204:207], v[8:11]
	v_mfma_f32_16x16x32_bf16 v[64:67], v[150:153], v[184:187], v[64:67]
	v_mfma_f32_16x16x32_bf16 v[56:59], v[176:179], v[184:187], v[56:59]
	v_mfma_f32_16x16x32_bf16 v[48:51], v[150:153], v[192:195], v[48:51]
	v_mfma_f32_16x16x32_bf16 v[40:43], v[176:179], v[192:195], v[40:43]
	v_mfma_f32_16x16x32_bf16 v[32:35], v[150:153], v[200:203], v[32:35]
	v_mfma_f32_16x16x32_bf16 v[24:27], v[176:179], v[200:203], v[24:27]
	s_barrier
	s_setprio 3
	v_mfma_f32_16x16x32_bf16 v[16:19], v[150:153], v[208:211], v[16:19]
	v_mfma_f32_16x16x32_bf16 v[8:11], v[176:179], v[208:211], v[8:11]
	s_setprio 2
	ds_read_b128 v[146:149], v228 offset:32768
	ds_read_b128 v[150:153], v228 offset:33792
	ds_read_b128 v[154:157], v228 offset:34816
	ds_read_b128 v[176:179], v228 offset:35840
	s_add_u32 s72, s54, 0x4000
	s_addc_u32 s73, s55, 0
	s_add_i32 s71, s74, s28
	s_mov_b32 m0, s71
	s_nop 0
	global_load_lds_dwordx4 v138, s[72:73]
	s_add_i32 m0, s71, 0x2000
	s_nop 0
	global_load_lds_dwordx4 v140, s[72:73]
	s_waitcnt vmcnt(6)
	s_barrier
; #define PG8_STAGE(bufoff, gbase, voff) do { _Pragma("unroll") for (int _i = 0; _i < 2; ++_i) \
;         __builtin_amdgcn_global_load_lds((const unsigned*)((const char*)(gbase) + (voff)[_i]), (LAS unsigned*)(lds + (bufoff) + ldsw + _i * 8192), 16, 0, 0); } while (0)
; #define PG8_LDA(dst, b, h) do { _Pragma("unroll") for (int m = 0; m < 4; ++m) _Pragma("unroll") for (int k = 0; k < 2; ++k) dst[m][k] = *(const LAS bf16x8*)(lds + PG8_SA(b, h) + aoff + m * 2048 + k * 1024); } while (0)
; #define PG8_LDB(dst, b, h) do { _Pragma("unroll") for (int n = 0; n < 2; ++n) _Pragma("unroll") for (int k = 0; k < 2; ++k) dst[n][k] = *(const LAS bf16x8*)(lds + PG8_SB(b, h) + boff + n * 2048 + k * 1024); } while (0)
; #define PG8_MMA(ai, bj, At, Bt) do { __builtin_amdgcn_s_setprio(1); _Pragma("unroll") for (int m = 0; m < 4; ++m) _Pragma("unroll") for (int n = 0; n < 2; ++n) _Pragma("unroll") for (int k = 0; k < 2; ++k) \
;         acc[ai][bj][m][n] = __builtin_amdgcn_mfma_f32_16x16x32_bf16(Bt[n][k], At[m][k], acc[ai][bj][m][n], 0, 0, 0); __builtin_amdgcn_s_setprio(0); } while (0)
; #define PG8_WAIT_V(n) asm volatile("s_waitcnt vmcnt(" #n ")" ::: "memory")
; #define PG8_WAIT_L(n) asm volatile("s_waitcnt lgkmcnt(" #n ")" ::: "memory")
; #define PG8_BAR __builtin_amdgcn_s_barrier()
; #define PG8_SCHED __builtin_amdgcn_sched_barrier(0)
; template <class Epi, class Sched, int LD>
; __device__ __forceinline__ void gemm_phase(LAS unsigned char* lds, const Gemm g, const Sched& S, const Epi& E) {
;     ...
;             PG8_WAIT_V(6); PG8_BAR; PG8_MMA(1, 1, At, B1); PG8_BAR;
;             PG8_LDB(B0, 1, 0); PG8_SCHED; PG8_LDA(At, 1, 0); PG8_STAGE(PG8_SA(0, 1), a2 + hstep, voffA);
;             PG8_WAIT_L(8); PG8_BAR; PG8_WAIT_L(0); PG8_MMA(0, 0, At, B0); PG8_BAR; PG8_SCHED;
;             PG8_LDB(B1, 1, 1); PG8_STAGE(PG8_SB(1, 0), b3, voffB);
;             PG8_BAR; PG8_WAIT_L(0); PG8_MMA(0, 1, At, B1); PG8_BAR;
;             PG8_LDA(At, 1, 1); PG8_STAGE(PG8_SA(1, 0), a3, voffA);
;             PG8_BAR; PG8_WAIT_L(0); PG8_MMA(1, 0, At, B0); PG8_BAR; PG8_SCHED;
	s_setprio 0
	v_mfma_f32_16x16x32_bf16 v[60:63], v[212:215], v[180:183], v[60:63]
	v_mfma_f32_16x16x32_bf16 v[52:55], v[220:223], v[180:183], v[52:55]
	v_mfma_f32_16x16x32_bf16 v[44:47], v[212:215], v[188:191], v[44:47]
	v_mfma_f32_16x16x32_bf16 v[36:39], v[220:223], v[188:191], v[36:39]
	v_mfma_f32_16x16x32_bf16 v[28:31], v[212:215], v[196:199], v[28:31]
	v_mfma_f32_16x16x32_bf16 v[20:23], v[220:223], v[196:199], v[20:23]
	v_mfma_f32_16x16x32_bf16 v[12:15], v[212:215], v[204:207], v[12:15]
	v_mfma_f32_16x16x32_bf16 v[4:7], v[220:223], v[204:207], v[4:7]
	v_mfma_f32_16x16x32_bf16 v[60:63], v[216:219], v[184:187], v[60:63]
	v_mfma_f32_16x16x32_bf16 v[52:55], v[224:227], v[184:187], v[52:55]
	v_mfma_f32_16x16x32_bf16 v[44:47], v[216:219], v[192:195], v[44:47]
	v_mfma_f32_16x16x32_bf16 v[36:39], v[224:227], v[192:195], v[36:39]
	v_mfma_f32_16x16x32_bf16 v[28:31], v[216:219], v[200:203], v[28:31]
	v_mfma_f32_16x16x32_bf16 v[20:23], v[224:227], v[200:203], v[20:23]
	s_barrier
	s_setprio 3
	v_mfma_f32_16x16x32_bf16 v[12:15], v[216:219], v[208:211], v[12:15]
	v_mfma_f32_16x16x32_bf16 v[4:7], v[224:227], v[208:211], v[4:7]
	s_setprio 2
	s_add_i32 s71, 0, 0x18000
	s_add_u32 s4, s4, 0x4000
	s_addc_u32 s5, s5, 0
	s_mov_b32 m0, s52
	ds_read_b128 v[180:183], v144 offset:32768
	ds_read_b128 v[184:187], v144 offset:33792
	ds_read_b128 v[188:191], v144 offset:34816
	ds_read_b128 v[192:195], v144 offset:35840
	ds_read_b128 v[196:199], v144 offset:36864
	ds_read_b128 v[200:203], v144 offset:37888
	ds_read_b128 v[204:207], v144 offset:38912
	ds_read_b128 v[208:211], v144 offset:39936
	global_load_lds_dwordx4 v138, s[4:5]
	s_mov_b32 m0, s53
	s_nop 0
	global_load_lds_dwordx4 v140, s[4:5]
	s_waitcnt lgkmcnt(8)
	s_barrier
	s_waitcnt lgkmcnt(0)
	s_setprio 0
	v_mfma_f32_16x16x32_bf16 v[128:131], v[146:149], v[180:183], v[128:131]
	v_mfma_f32_16x16x32_bf16 v[120:123], v[154:157], v[180:183], v[120:123]
	v_mfma_f32_16x16x32_bf16 v[112:115], v[146:149], v[188:191], v[112:115]
	v_mfma_f32_16x16x32_bf16 v[104:107], v[154:157], v[188:191], v[104:107]
	v_mfma_f32_16x16x32_bf16 v[96:99], v[146:149], v[196:199], v[96:99]
	v_mfma_f32_16x16x32_bf16 v[88:91], v[154:157], v[196:199], v[88:91]
	v_mfma_f32_16x16x32_bf16 v[80:83], v[146:149], v[204:207], v[80:83]
	v_mfma_f32_16x16x32_bf16 v[72:75], v[154:157], v[204:207], v[72:75]
	v_mfma_f32_16x16x32_bf16 v[128:131], v[150:153], v[184:187], v[128:131]
	v_mfma_f32_16x16x32_bf16 v[120:123], v[176:179], v[184:187], v[120:123]
	v_mfma_f32_16x16x32_bf16 v[112:115], v[150:153], v[192:195], v[112:115]
	v_mfma_f32_16x16x32_bf16 v[104:107], v[176:179], v[192:195], v[104:107]
	v_mfma_f32_16x16x32_bf16 v[96:99], v[150:153], v[200:203], v[96:99]
	v_mfma_f32_16x16x32_bf16 v[88:91], v[176:179], v[200:203], v[88:91]
	s_barrier
	s_setprio 3
	v_mfma_f32_16x16x32_bf16 v[80:83], v[150:153], v[208:211], v[80:83]
	v_mfma_f32_16x16x32_bf16 v[72:75], v[176:179], v[208:211], v[72:75]
	s_setprio 2
	s_add_i32 s72, 0, 0x1c000
	s_add_u32 s4, s54, 0x8000
	s_addc_u32 s5, s55, 0
	s_add_i32 s71, s71, s28
	s_mov_b32 m0, s71
	ds_read_b128 v[212:215], v228 offset:49152
	ds_read_b128 v[216:219], v228 offset:50176
	ds_read_b128 v[220:223], v228 offset:51200
	ds_read_b128 v[224:227], v228 offset:52224
	global_load_lds_dwordx4 v138, s[4:5]
	s_add_i32 m0, s71, 0x2000
	s_nop 0
	global_load_lds_dwordx4 v140, s[4:5]
	s_barrier
	s_waitcnt lgkmcnt(0)
	s_setprio 0
	v_mfma_f32_16x16x32_bf16 v[124:127], v[212:215], v[180:183], v[124:127]
	v_mfma_f32_16x16x32_bf16 v[116:119], v[220:223], v[180:183], v[116:119]
	v_mfma_f32_16x16x32_bf16 v[108:111], v[212:215], v[188:191], v[108:111]
	v_mfma_f32_16x16x32_bf16 v[100:103], v[220:223], v[188:191], v[100:103]
	v_mfma_f32_16x16x32_bf16 v[92:95], v[212:215], v[196:199], v[92:95]
	v_mfma_f32_16x16x32_bf16 v[84:87], v[220:223], v[196:199], v[84:87]
	v_mfma_f32_16x16x32_bf16 v[76:79], v[212:215], v[204:207], v[76:79]
	v_mfma_f32_16x16x32_bf16 v[68:71], v[220:223], v[204:207], v[68:71]
	v_mfma_f32_16x16x32_bf16 v[124:127], v[216:219], v[184:187], v[124:127]
	v_mfma_f32_16x16x32_bf16 v[116:119], v[224:227], v[184:187], v[116:119]
	v_mfma_f32_16x16x32_bf16 v[108:111], v[216:219], v[192:195], v[108:111]
	v_mfma_f32_16x16x32_bf16 v[100:103], v[224:227], v[192:195], v[100:103]
	v_mfma_f32_16x16x32_bf16 v[92:95], v[216:219], v[200:203], v[92:95]
	v_mfma_f32_16x16x32_bf16 v[84:87], v[224:227], v[200:203], v[84:87]
	s_barrier
	s_setprio 3
	v_mfma_f32_16x16x32_bf16 v[76:79], v[216:219], v[208:211], v[76:79]
	v_mfma_f32_16x16x32_bf16 v[68:71], v[224:227], v[208:211], v[68:71]
	s_setprio 2
	s_mov_b32 m0, s60
	ds_read_b128 v[180:183], v144 offset:49152
	ds_read_b128 v[184:187], v144 offset:50176
	ds_read_b128 v[188:191], v144 offset:51200
	ds_read_b128 v[192:195], v144 offset:52224
	ds_read_b128 v[196:199], v144 offset:53248
	ds_read_b128 v[200:203], v144 offset:54272
	ds_read_b128 v[204:207], v144 offset:55296
	ds_read_b128 v[208:211], v144 offset:56320
	global_load_lds_dwordx4 v138, s[56:57]
	s_mov_b32 m0, s61
	s_nop 0
	global_load_lds_dwordx4 v140, s[56:57]
	s_waitcnt vmcnt(10)
	s_barrier
	s_waitcnt lgkmcnt(0)
	s_setprio 0
	v_mfma_f32_16x16x32_bf16 v[64:67], v[146:149], v[180:183], v[64:67]
	v_mfma_f32_16x16x32_bf16 v[56:59], v[154:157], v[180:183], v[56:59]
	v_mfma_f32_16x16x32_bf16 v[48:51], v[146:149], v[188:191], v[48:51]
	v_mfma_f32_16x16x32_bf16 v[40:43], v[154:157], v[188:191], v[40:43]
	v_mfma_f32_16x16x32_bf16 v[32:35], v[146:149], v[196:199], v[32:35]
	v_mfma_f32_16x16x32_bf16 v[24:27], v[154:157], v[196:199], v[24:27]
	v_mfma_f32_16x16x32_bf16 v[16:19], v[146:149], v[204:207], v[16:19]
	v_mfma_f32_16x16x32_bf16 v[8:11], v[154:157], v[204:207], v[8:11]
	v_mfma_f32_16x16x32_bf16 v[64:67], v[150:153], v[184:187], v[64:67]
	v_mfma_f32_16x16x32_bf16 v[56:59], v[176:179], v[184:187], v[56:59]
	v_mfma_f32_16x16x32_bf16 v[48:51], v[150:153], v[192:195], v[48:51]
	v_mfma_f32_16x16x32_bf16 v[40:43], v[176:179], v[192:195], v[40:43]
	v_mfma_f32_16x16x32_bf16 v[32:35], v[150:153], v[200:203], v[32:35]
	v_mfma_f32_16x16x32_bf16 v[24:27], v[176:179], v[200:203], v[24:27]
	s_barrier
; __device__ __forceinline__ unsigned cvt_pk_bf16(float lo, float hi) { f32x2 v = {lo, hi}; bf16x2v b = __builtin_convertvector(v, bf16x2v); return __builtin_bit_cast(unsigned, b); }
; __device__ __forceinline__ float silu_f(float x) { return x * __builtin_amdgcn_rcpf(1.f + __expf(-x)); }
; #define PG8_STAGE(bufoff, gbase, voff) do { _Pragma("unroll") for (int _i = 0; _i < 2; ++_i) \
;         __builtin_amdgcn_global_load_lds((const unsigned*)((const char*)(gbase) + (voff)[_i]), (LAS unsigned*)(lds + (bufoff) + ldsw + _i * 8192), 16, 0, 0); } while (0)
; #define PG8_MMA(ai, bj, At, Bt) do { __builtin_amdgcn_s_setprio(1); _Pragma("unroll") for (int m = 0; m < 4; ++m) _Pragma("unroll") for (int n = 0; n < 2; ++n) _Pragma("unroll") for (int k = 0; k < 2; ++k) \
;         acc[ai][bj][m][n] = __builtin_amdgcn_mfma_f32_16x16x32_bf16(Bt[n][k], At[m][k], acc[ai][bj][m][n], 0, 0, 0); __builtin_amdgcn_s_setprio(0); } while (0)
; #define PG8_WAIT_V(n) asm volatile("s_waitcnt vmcnt(" #n ")" ::: "memory")
; #define PG8_WAIT_L(n) asm volatile("s_waitcnt lgkmcnt(" #n ")" ::: "memory")
;     __device__ __forceinline__ void operator()(const f32x4 (&acc)[2][2][4][2], const Unit& u, int wr, int wc, int fr, int fq) const {
;         const int row0 = u.pm * BM + wr * 64 + fr, col0 = u.pn * 128 + wc * 32 + 8 * fq;
; #pragma unroll
;         for (int ai = 0; ai < 2; ++ai)
; #pragma unroll
;             for (int m = 0; m < 4; ++m) {
;                 bf16_t* rowp = O + img_off(row0 + ai * HALF + m * 16, col0, D_FF / 64);
;                 const f32x4 g0 = acc[ai][0][m][0], g1 = acc[ai][0][m][1], u0 = acc[ai][1][m][0], u1 = acc[ai][1][m][1];
;                 u32x4 w;
;                 w.x = cvt_pk_bf16(silu_f(g0[0]) * u0[0], silu_f(g0[1]) * u0[1]); w.y = cvt_pk_bf16(silu_f(g0[2]) * u0[2], silu_f(g0[3]) * u0[3]);
;                 w.z = cvt_pk_bf16(silu_f(g1[0]) * u1[0], silu_f(g1[1]) * u1[1]); w.w = cvt_pk_bf16(silu_f(g1[2]) * u1[2], silu_f(g1[3]) * u1[3]);
;                 *(u32x4*)rowp = w;
; template <class Epi, class Sched, int LD>
; __device__ __forceinline__ void gemm_phase(LAS unsigned char* lds, const Gemm g, const Sched& S, const Epi& E) {
;     ...
;             PG8_BAR; PG8_WAIT_L(0); PG8_MMA(1, 0, At, B0); PG8_BAR; PG8_SCHED;
;             PG8_STAGE(PG8_SB(1, 1), b3 + hstep, voffB);
;             PG8_WAIT_V(6); PG8_BAR; PG8_MMA(1, 1, At, B1); PG8_BAR;
	s_setprio 3
	v_mfma_f32_16x16x32_bf16 v[16:19], v[150:153], v[208:211], v[16:19]
	v_mfma_f32_16x16x32_bf16 v[8:11], v[176:179], v[208:211], v[8:11]
	s_setprio 2
	ds_read_b128 v[146:149], v228
	ds_read_b128 v[150:153], v228 offset:1024
	ds_read_b128 v[154:157], v228 offset:2048
	ds_read_b128 v[176:179], v228 offset:3072
	s_add_u32 s4, s54, 0xc000
	s_addc_u32 s5, s55, 0
	s_add_i32 s54, s72, s28
	s_mov_b32 m0, s54
	s_nop 0
	global_load_lds_dwordx4 v138, s[4:5]
	s_add_i32 m0, s54, 0x2000
	s_nop 0
	global_load_lds_dwordx4 v140, s[4:5]
	s_waitcnt vmcnt(6)
	s_barrier
	s_setprio 0
	v_mfma_f32_16x16x32_bf16 v[60:63], v[212:215], v[180:183], v[60:63]
	v_mfma_f32_16x16x32_bf16 v[52:55], v[220:223], v[180:183], v[52:55]
	v_mfma_f32_16x16x32_bf16 v[44:47], v[212:215], v[188:191], v[44:47]
	v_mfma_f32_16x16x32_bf16 v[36:39], v[220:223], v[188:191], v[36:39]
	v_mfma_f32_16x16x32_bf16 v[28:31], v[212:215], v[196:199], v[28:31]
	v_mfma_f32_16x16x32_bf16 v[20:23], v[220:223], v[196:199], v[20:23]
	v_mfma_f32_16x16x32_bf16 v[12:15], v[212:215], v[204:207], v[12:15]
	v_mfma_f32_16x16x32_bf16 v[4:7], v[220:223], v[204:207], v[4:7]
	v_mfma_f32_16x16x32_bf16 v[60:63], v[216:219], v[184:187], v[60:63]
	v_mfma_f32_16x16x32_bf16 v[52:55], v[224:227], v[184:187], v[52:55]
	v_mfma_f32_16x16x32_bf16 v[44:47], v[216:219], v[192:195], v[44:47]
	v_mfma_f32_16x16x32_bf16 v[36:39], v[224:227], v[192:195], v[36:39]
	v_mfma_f32_16x16x32_bf16 v[28:31], v[216:219], v[200:203], v[28:31]
	v_mfma_f32_16x16x32_bf16 v[20:23], v[224:227], v[200:203], v[20:23]
	s_barrier
	s_setprio 3
	v_mfma_f32_16x16x32_bf16 v[12:15], v[216:219], v[208:211], v[12:15]
	v_mfma_f32_16x16x32_bf16 v[4:7], v[224:227], v[208:211], v[4:7]
	s_setprio 2
	s_add_i32 s70, s70, 2
	s_add_u32 s50, s50, 0x10000
	s_addc_u32 s51, s51, 0
	s_add_u32 s45, s45, 0x10000
	s_addc_u32 s47, s47, 0
	s_cmp_gt_u32 s70, 29
	s_cbranch_scc0 .LBB0_899
	s_setprio 0
	v_mul_f32_e32 v148, 0xbfb8aa3b, v128
	v_mul_f32_e32 v149, 0xbfb8aa3b, v129
	v_exp_f32_e32 v148, v148
	v_exp_f32_e32 v149, v149
	s_lshl_b32 s5, s69, 8
	s_add_i32 s5, s5, s58
	v_add_f32_e32 v148, 1.0, v148
	v_add_f32_e32 v149, 1.0, v149
	v_rcp_f32_e32 v148, v148
	v_rcp_f32_e32 v149, v149
	s_lshl_b32 s4, s68, 7
	s_or_b32 s4, s4, s59
	s_ashr_i32 s45, s5, 8
	v_pk_mul_f32 v[128:129], v[128:129], v[148:149]
	s_ashr_i32 s4, s4, 6
	v_pk_mul_f32 v[124:125], v[128:129], v[124:125]
	s_mulk_i32 s45, 0x58
	v_cvt_pk_bf16_f32 v124, v124, v125
	v_mul_f32_e32 v125, 0xbfb8aa3b, v130
	v_exp_f32_e32 v125, v125
	s_add_i32 s50, s45, s4
	s_ashr_i32 s51, s50, 31
	s_lshl_b64 s[50:51], s[50:51], 15
	v_add_f32_e32 v125, 1.0, v125
	v_rcp_f32_e32 v128, v125
	v_mul_f32_e32 v125, 0xbfb8aa3b, v131
	v_exp_f32_e32 v125, v125
	s_add_u32 s45, s16, s50
	s_addc_u32 s47, s17, s51
	s_lshl_b32 s50, s5, 7
	v_add_f32_e32 v125, 1.0, v125
	v_rcp_f32_e32 v129, v125
	s_and_b32 s50, s50, 0x4000
	s_add_u32 s50, s45, s50
	s_addc_u32 s51, s47, 0
	v_pk_mul_f32 v[128:129], v[130:131], v[128:129]
	s_or_b32 s45, s5, 16
	v_pk_mul_f32 v[126:127], v[128:129], v[126:127]
	s_lshr_b32 s45, s45, 3
	v_cvt_pk_bf16_f32 v125, v126, v127
	v_mul_f32_e32 v126, 0xbfb8aa3b, v120
	v_mul_f32_e32 v127, 0xbfb8aa3b, v121
	v_exp_f32_e32 v126, v126
	v_exp_f32_e32 v127, v127
	v_or_b32_e32 v145, s5, v137
	s_and_b32 s45, s45, 10
	v_add_f32_e32 v126, 1.0, v126
	v_add_f32_e32 v127, 1.0, v127
	v_rcp_f32_e32 v126, v126
	v_rcp_f32_e32 v127, v127
	v_lshlrev_b32_e32 v132, 6, v145
	v_lshlrev_b32_e32 v146, 2, v145
	s_or_b32 s45, s45, s64
	v_pk_mul_f32 v[120:121], v[120:121], v[126:127]
	v_and_or_b32 v132, v132, s15, v142
	v_pk_mul_f32 v[116:117], v[120:121], v[116:117]
	v_and_b32_e32 v146, 32, v146
	v_cvt_pk_bf16_f32 v126, v116, v117
	v_mul_f32_e32 v116, 0xbfb8aa3b, v122
	v_mul_f32_e32 v117, 0xbfb8aa3b, v123
	v_exp_f32_e32 v116, v116
	v_exp_f32_e32 v117, v117
	s_lshl_b32 s45, s45, 10
	v_bitop3_b32 v147, v132, s65, v146 bitop3:0xde
	v_add_f32_e32 v116, 1.0, v116
	v_add_f32_e32 v117, 1.0, v117
	v_rcp_f32_e32 v116, v116
	v_rcp_f32_e32 v117, v117
	s_and_b64 vcc, exec, s[42:43]
	s_mov_b32 s68, s44
	s_mov_b32 s69, s46
	v_pk_mul_f32 v[116:117], v[122:123], v[116:117]
	s_mov_b64 s[54:55], s[40:41]
	v_pk_mul_f32 v[116:117], v[116:117], v[118:119]
	v_bitop3_b32 v118, v132, s45, v146 bitop3:0xde
	v_cvt_pk_bf16_f32 v127, v116, v117
	v_mul_f32_e32 v116, 0xbfb8aa3b, v112
	v_mul_f32_e32 v117, 0xbfb8aa3b, v113
	v_exp_f32_e32 v116, v116
	v_exp_f32_e32 v117, v117
	s_or_b32 s45, s5, 32
	s_or_b32 s5, s5, 48
	v_add_f32_e32 v116, 1.0, v116
	v_add_f32_e32 v117, 1.0, v117
	v_rcp_f32_e32 v116, v116
	v_rcp_f32_e32 v117, v117
	s_lshr_b32 s45, s45, 3
	s_lshr_b32 s5, s5, 3
	s_and_b32 s45, s45, 12
	v_pk_mul_f32 v[112:113], v[112:113], v[116:117]
	s_and_b32 s5, s5, 14
	v_pk_mul_f32 v[108:109], v[112:113], v[108:109]
	s_or_b32 s45, s45, s64
	v_cvt_pk_bf16_f32 v108, v108, v109
	v_mul_f32_e32 v109, 0xbfb8aa3b, v114
	v_exp_f32_e32 v109, v109
	s_or_b32 s5, s5, s64
	s_lshl_b32 s45, s45, 10
	s_lshl_b32 s5, s5, 10
	v_add_f32_e32 v109, 1.0, v109
	v_rcp_f32_e32 v112, v109
	v_mul_f32_e32 v109, 0xbfb8aa3b, v115
	v_exp_f32_e32 v109, v109
	global_store_dwordx4 v147, v[124:127], s[50:51]
	v_add_f32_e32 v109, 1.0, v109
	v_rcp_f32_e32 v113, v109
	s_nop 0
	v_pk_mul_f32 v[112:113], v[114:115], v[112:113]
	s_nop 0
	v_pk_mul_f32 v[110:111], v[112:113], v[110:111]
	s_nop 0
	v_cvt_pk_bf16_f32 v109, v110, v111
	v_mul_f32_e32 v110, 0xbfb8aa3b, v104
	v_mul_f32_e32 v111, 0xbfb8aa3b, v105
	v_exp_f32_e32 v110, v110
	v_exp_f32_e32 v111, v111
	v_add_f32_e32 v110, 1.0, v110
	v_add_f32_e32 v111, 1.0, v111
	v_rcp_f32_e32 v110, v110
	v_rcp_f32_e32 v111, v111
	s_nop 0
	v_pk_mul_f32 v[104:105], v[104:105], v[110:111]
	s_nop 0
; __device__ __forceinline__ unsigned cvt_pk_bf16(float lo, float hi) { f32x2 v = {lo, hi}; bf16x2v b = __builtin_convertvector(v, bf16x2v); return __builtin_bit_cast(unsigned, b); }
; __device__ __forceinline__ float silu_f(float x) { return x * __builtin_amdgcn_rcpf(1.f + __expf(-x)); }
;     __device__ __forceinline__ void operator()(const f32x4 (&acc)[2][2][4][2], const Unit& u, int wr, int wc, int fr, int fq) const {
;     ...
;                 bf16_t* rowp = O + img_off(row0 + ai * HALF + m * 16, col0, D_FF / 64);
;                 const f32x4 g0 = acc[ai][0][m][0], g1 = acc[ai][0][m][1], u0 = acc[ai][1][m][0], u1 = acc[ai][1][m][1];
;                 u32x4 w;
;                 w.x = cvt_pk_bf16(silu_f(g0[0]) * u0[0], silu_f(g0[1]) * u0[1]); w.y = cvt_pk_bf16(silu_f(g0[2]) * u0[2], silu_f(g0[3]) * u0[3]);
;                 w.z = cvt_pk_bf16(silu_f(g1[0]) * u1[0], silu_f(g1[1]) * u1[1]); w.w = cvt_pk_bf16(silu_f(g1[2]) * u1[2], silu_f(g1[3]) * u1[3]);
;                 *(u32x4*)rowp = w;
	v_pk_mul_f32 v[100:101], v[104:105], v[100:101]
	s_nop 0
	v_cvt_pk_bf16_f32 v110, v100, v101
	v_mul_f32_e32 v100, 0xbfb8aa3b, v106
	v_mul_f32_e32 v101, 0xbfb8aa3b, v107
	v_exp_f32_e32 v100, v100
	v_exp_f32_e32 v101, v101
	v_add_f32_e32 v100, 1.0, v100
	v_add_f32_e32 v101, 1.0, v101
	v_rcp_f32_e32 v100, v100
	v_rcp_f32_e32 v101, v101
	s_nop 0
	v_pk_mul_f32 v[100:101], v[106:107], v[100:101]
	s_nop 0
	v_pk_mul_f32 v[100:101], v[100:101], v[102:103]
	v_bitop3_b32 v102, v132, s45, v146 bitop3:0xde
	v_cvt_pk_bf16_f32 v111, v100, v101
	v_mul_f32_e32 v100, 0xbfb8aa3b, v96
	v_mul_f32_e32 v101, 0xbfb8aa3b, v97
	v_exp_f32_e32 v100, v100
	v_exp_f32_e32 v101, v101
	global_store_dwordx4 v118, v[108:111], s[50:51]
	v_add_f32_e32 v100, 1.0, v100
	v_add_f32_e32 v101, 1.0, v101
	v_rcp_f32_e32 v100, v100
	v_rcp_f32_e32 v101, v101
	s_nop 0
	v_pk_mul_f32 v[96:97], v[96:97], v[100:101]
	s_nop 0
	v_pk_mul_f32 v[92:93], v[96:97], v[92:93]
	s_nop 0
	v_cvt_pk_bf16_f32 v92, v92, v93
	v_mul_f32_e32 v93, 0xbfb8aa3b, v98
	v_exp_f32_e32 v93, v93
	s_nop 0
	v_add_f32_e32 v93, 1.0, v93
	v_rcp_f32_e32 v96, v93
	v_mul_f32_e32 v93, 0xbfb8aa3b, v99
	v_exp_f32_e32 v93, v93
	s_nop 0
	v_add_f32_e32 v93, 1.0, v93
	v_rcp_f32_e32 v97, v93
	s_nop 0
	v_pk_mul_f32 v[96:97], v[98:99], v[96:97]
	s_nop 0
	v_pk_mul_f32 v[94:95], v[96:97], v[94:95]
	s_nop 0
	v_cvt_pk_bf16_f32 v93, v94, v95
	v_mul_f32_e32 v94, 0xbfb8aa3b, v88
	v_mul_f32_e32 v95, 0xbfb8aa3b, v89
	v_exp_f32_e32 v94, v94
	v_exp_f32_e32 v95, v95
	v_add_f32_e32 v94, 1.0, v94
	v_add_f32_e32 v95, 1.0, v95
	v_rcp_f32_e32 v94, v94
	v_rcp_f32_e32 v95, v95
	s_nop 0
	v_pk_mul_f32 v[88:89], v[88:89], v[94:95]
	s_nop 0
	v_pk_mul_f32 v[84:85], v[88:89], v[84:85]
	s_nop 0
	v_cvt_pk_bf16_f32 v94, v84, v85
	v_mul_f32_e32 v84, 0xbfb8aa3b, v90
	v_mul_f32_e32 v85, 0xbfb8aa3b, v91
	v_exp_f32_e32 v84, v84
	v_exp_f32_e32 v85, v85
	v_add_f32_e32 v84, 1.0, v84
	v_add_f32_e32 v85, 1.0, v85
	v_rcp_f32_e32 v84, v84
	v_rcp_f32_e32 v85, v85
	s_nop 0
	v_pk_mul_f32 v[84:85], v[90:91], v[84:85]
	s_nop 0
	v_pk_mul_f32 v[84:85], v[84:85], v[86:87]
	v_bitop3_b32 v86, v132, s5, v146 bitop3:0xde
	v_cvt_pk_bf16_f32 v95, v84, v85
	v_mul_f32_e32 v84, 0xbfb8aa3b, v80
	v_mul_f32_e32 v85, 0xbfb8aa3b, v81
	v_exp_f32_e32 v84, v84
	v_exp_f32_e32 v85, v85
	global_store_dwordx4 v102, v[92:95], s[50:51]
	v_add_f32_e32 v84, 1.0, v84
	v_add_f32_e32 v85, 1.0, v85
	v_rcp_f32_e32 v84, v84
	v_rcp_f32_e32 v85, v85
	s_nop 0
	v_pk_mul_f32 v[80:81], v[80:81], v[84:85]
	s_nop 0
	v_pk_mul_f32 v[76:77], v[80:81], v[76:77]
	s_nop 0
	v_cvt_pk_bf16_f32 v76, v76, v77
	v_mul_f32_e32 v77, 0xbfb8aa3b, v82
	v_exp_f32_e32 v77, v77
	s_nop 0
	v_add_f32_e32 v77, 1.0, v77
	v_rcp_f32_e32 v80, v77
	v_mul_f32_e32 v77, 0xbfb8aa3b, v83
	v_exp_f32_e32 v77, v77
	s_nop 0
	v_add_f32_e32 v77, 1.0, v77
	v_rcp_f32_e32 v81, v77
	s_nop 0
	v_pk_mul_f32 v[80:81], v[82:83], v[80:81]
	s_nop 0
	v_pk_mul_f32 v[78:79], v[80:81], v[78:79]
	s_nop 0
	v_cvt_pk_bf16_f32 v77, v78, v79
	v_mul_f32_e32 v78, 0xbfb8aa3b, v72
	v_mul_f32_e32 v79, 0xbfb8aa3b, v73
	v_exp_f32_e32 v78, v78
	v_exp_f32_e32 v79, v79
	v_add_f32_e32 v78, 1.0, v78
	v_add_f32_e32 v79, 1.0, v79
	v_rcp_f32_e32 v78, v78
	v_rcp_f32_e32 v79, v79
	s_nop 0
	v_pk_mul_f32 v[72:73], v[72:73], v[78:79]
	s_nop 0
	v_pk_mul_f32 v[68:69], v[72:73], v[68:69]
	v_mul_f32_e32 v73, 0xbfb8aa3b, v65
	v_cvt_pk_bf16_f32 v78, v68, v69
	v_mul_f32_e32 v68, 0xbfb8aa3b, v74
	v_mul_f32_e32 v69, 0xbfb8aa3b, v75
	v_exp_f32_e32 v68, v68
	v_exp_f32_e32 v69, v69
	v_exp_f32_e32 v73, v73
	v_add_f32_e32 v68, 1.0, v68
	v_add_f32_e32 v69, 1.0, v69
	v_rcp_f32_e32 v68, v68
	v_rcp_f32_e32 v69, v69
	v_add_f32_e32 v73, 1.0, v73
	v_rcp_f32_e32 v73, v73
	v_pk_mul_f32 v[68:69], v[74:75], v[68:69]
	s_nop 0
	v_pk_mul_f32 v[68:69], v[68:69], v[70:71]
	v_add_u32_e32 v70, 0x80, v145
	v_lshlrev_b32_e32 v71, 6, v70
	v_lshlrev_b32_e32 v72, 2, v70
	v_and_or_b32 v71, v71, s15, v142
	v_and_b32_e32 v72, 32, v72
	v_bitop3_b32 v132, v71, s65, v72 bitop3:0xde
	v_mul_f32_e32 v72, 0xbfb8aa3b, v64
	v_exp_f32_e32 v72, v72
	v_cvt_pk_bf16_f32 v79, v68, v69
	v_lshrrev_b32_e32 v68, 8, v70
	v_mov_b32_e32 v69, s4
	v_add_f32_e32 v72, 1.0, v72
	v_rcp_f32_e32 v72, v72
	s_movk_i32 s4, 0x58
	v_mad_i32_i24 v68, v68, s4, v69
	v_ashrrev_i32_e32 v69, 31, v68
	v_pk_mul_f32 v[64:65], v[64:65], v[72:73]
	v_lshlrev_b64 v[68:69], 15, v[68:69]
	v_pk_mul_f32 v[60:61], v[64:65], v[60:61]
	v_lshlrev_b32_e32 v70, 7, v70
	v_cvt_pk_bf16_f32 v60, v60, v61
	v_mul_f32_e32 v61, 0xbfb8aa3b, v66
	v_exp_f32_e32 v61, v61
	v_lshl_add_u64 v[68:69], s[16:17], 0, v[68:69]
	v_and_b32_e32 v70, 0x4000, v70
	v_mov_b32_e32 v71, v133
	v_add_f32_e32 v61, 1.0, v61
	v_rcp_f32_e32 v64, v61
	v_mul_f32_e32 v61, 0xbfb8aa3b, v67
	v_exp_f32_e32 v61, v61
	v_lshl_add_u64 v[70:71], v[68:69], 0, v[70:71]
	v_lshl_add_u64 v[70:71], v[70:71], 0, v[132:133]
	s_mov_b64 s[4:5], s[48:49]
	v_add_f32_e32 v61, 1.0, v61
	v_rcp_f32_e32 v65, v61
	global_store_dwordx4 v86, v[76:79], s[50:51]
	v_pk_mul_f32 v[64:65], v[66:67], v[64:65]
	s_nop 0
	v_pk_mul_f32 v[62:63], v[64:65], v[62:63]
	s_nop 0
	v_cvt_pk_bf16_f32 v61, v62, v63
	v_mul_f32_e32 v62, 0xbfb8aa3b, v56
	v_mul_f32_e32 v63, 0xbfb8aa3b, v57
	v_exp_f32_e32 v62, v62
	v_exp_f32_e32 v63, v63
	v_add_f32_e32 v62, 1.0, v62
	v_add_f32_e32 v63, 1.0, v63
	v_rcp_f32_e32 v62, v62
	v_rcp_f32_e32 v63, v63
	s_nop 0
	v_pk_mul_f32 v[56:57], v[56:57], v[62:63]
	s_nop 0
	v_pk_mul_f32 v[52:53], v[56:57], v[52:53]
	s_nop 0
	v_cvt_pk_bf16_f32 v62, v52, v53
	v_mul_f32_e32 v52, 0xbfb8aa3b, v58
	v_mul_f32_e32 v53, 0xbfb8aa3b, v59
	v_exp_f32_e32 v52, v52
	v_exp_f32_e32 v53, v53
	v_add_f32_e32 v52, 1.0, v52
	v_add_f32_e32 v53, 1.0, v53
	v_rcp_f32_e32 v52, v52
; __device__ __forceinline__ unsigned cvt_pk_bf16(float lo, float hi) { f32x2 v = {lo, hi}; bf16x2v b = __builtin_convertvector(v, bf16x2v); return __builtin_bit_cast(unsigned, b); }
; __device__ __forceinline__ float silu_f(float x) { return x * __builtin_amdgcn_rcpf(1.f + __expf(-x)); }
; #define PG8_WAIT_V(n) asm volatile("s_waitcnt vmcnt(" #n ")" ::: "memory")
; #define PG8_BAR __builtin_amdgcn_s_barrier()
;     __device__ __forceinline__ void operator()(const f32x4 (&acc)[2][2][4][2], const Unit& u, int wr, int wc, int fr, int fq) const {
;     ...
;                 bf16_t* rowp = O + img_off(row0 + ai * HALF + m * 16, col0, D_FF / 64);
;                 const f32x4 g0 = acc[ai][0][m][0], g1 = acc[ai][0][m][1], u0 = acc[ai][1][m][0], u1 = acc[ai][1][m][1];
;                 u32x4 w;
;                 w.x = cvt_pk_bf16(silu_f(g0[0]) * u0[0], silu_f(g0[1]) * u0[1]); w.y = cvt_pk_bf16(silu_f(g0[2]) * u0[2], silu_f(g0[3]) * u0[3]);
;                 w.z = cvt_pk_bf16(silu_f(g1[0]) * u1[0], silu_f(g1[1]) * u1[1]); w.w = cvt_pk_bf16(silu_f(g1[2]) * u1[2], silu_f(g1[3]) * u1[3]);
;                 *(u32x4*)rowp = w;
; template <class Epi, class Sched, int LD>
; __device__ __forceinline__ void gemm_phase(LAS unsigned char* lds, const Gemm g, const Sched& S, const Epi& E) {
;     ...
;         E(acc, cur, wr, wc, fr, fq);
;         if (!has_next) break;
; #pragma unroll
;         for (int a = 0; a < 2; ++a)
; #pragma unroll
;             for (int b = 0; b < 2; ++b)
; #pragma unroll
;                 for (int m = 0; m < 4; ++m)
; #pragma unroll
;                     for (int n = 0; n < 2; ++n) acc[a][b][m][n] = (f32x4){0.f, 0.f, 0.f, 0.f};
;         cur = nxt; cA = nA; cB = nB; ++ui;
;     }
;     PG8_WAIT_V(0);
;     if (wr == 0) PG8_BAR;
	v_rcp_f32_e32 v53, v53
	s_nop 0
	v_pk_mul_f32 v[52:53], v[58:59], v[52:53]
	s_nop 0
	v_pk_mul_f32 v[52:53], v[52:53], v[54:55]
	s_nop 0
	v_cvt_pk_bf16_f32 v63, v52, v53
	v_add_u32_e32 v52, 0x90, v145
	v_lshrrev_b32_e32 v54, 3, v52
	v_lshlrev_b32_e32 v53, 6, v52
	v_and_or_b32 v54, v54, 10, s64
	v_lshlrev_b32_e32 v55, 2, v52
	v_and_or_b32 v53, v53, s15, v142
	v_lshlrev_b32_e32 v54, 10, v54
	v_and_b32_e32 v55, 32, v55
	v_bitop3_b32 v132, v53, v54, v55 bitop3:0xde
	v_mul_f32_e32 v54, 0xbfb8aa3b, v48
	v_mul_f32_e32 v55, 0xbfb8aa3b, v49
	v_exp_f32_e32 v54, v54
	v_exp_f32_e32 v55, v55
	v_lshlrev_b32_e32 v52, 7, v52
	v_and_b32_e32 v52, 0x4000, v52
	v_add_f32_e32 v54, 1.0, v54
	v_add_f32_e32 v55, 1.0, v55
	v_rcp_f32_e32 v54, v54
	v_rcp_f32_e32 v55, v55
	v_mov_b32_e32 v53, v133
	v_lshl_add_u64 v[52:53], v[68:69], 0, v[52:53]
	v_lshl_add_u64 v[52:53], v[52:53], 0, v[132:133]
	v_pk_mul_f32 v[48:49], v[48:49], v[54:55]
	global_store_dwordx4 v[70:71], v[60:63], off
	v_pk_mul_f32 v[44:45], v[48:49], v[44:45]
	s_nop 0
	v_cvt_pk_bf16_f32 v44, v44, v45
	v_mul_f32_e32 v45, 0xbfb8aa3b, v50
	v_exp_f32_e32 v45, v45
	s_nop 0
	v_add_f32_e32 v45, 1.0, v45
	v_rcp_f32_e32 v48, v45
	v_mul_f32_e32 v45, 0xbfb8aa3b, v51
	v_exp_f32_e32 v45, v45
	s_nop 0
	v_add_f32_e32 v45, 1.0, v45
	v_rcp_f32_e32 v49, v45
	s_nop 0
	v_pk_mul_f32 v[48:49], v[50:51], v[48:49]
	s_nop 0
	v_pk_mul_f32 v[46:47], v[48:49], v[46:47]
	s_nop 0
	v_cvt_pk_bf16_f32 v45, v46, v47
	v_mul_f32_e32 v46, 0xbfb8aa3b, v40
	v_mul_f32_e32 v47, 0xbfb8aa3b, v41
	v_exp_f32_e32 v46, v46
	v_exp_f32_e32 v47, v47
	v_add_f32_e32 v46, 1.0, v46
	v_add_f32_e32 v47, 1.0, v47
	v_rcp_f32_e32 v46, v46
	v_rcp_f32_e32 v47, v47
	s_nop 0
	v_pk_mul_f32 v[40:41], v[40:41], v[46:47]
	s_nop 0
	v_pk_mul_f32 v[36:37], v[40:41], v[36:37]
	s_nop 0
	v_cvt_pk_bf16_f32 v46, v36, v37
	v_mul_f32_e32 v36, 0xbfb8aa3b, v42
	v_mul_f32_e32 v37, 0xbfb8aa3b, v43
	v_exp_f32_e32 v36, v36
	v_exp_f32_e32 v37, v37
	v_add_f32_e32 v36, 1.0, v36
	v_add_f32_e32 v37, 1.0, v37
	v_rcp_f32_e32 v36, v36
	v_rcp_f32_e32 v37, v37
	s_nop 0
	v_pk_mul_f32 v[36:37], v[42:43], v[36:37]
	s_nop 0
	v_pk_mul_f32 v[36:37], v[36:37], v[38:39]
	s_nop 0
	v_cvt_pk_bf16_f32 v47, v36, v37
	v_add_u32_e32 v36, 0xa0, v145
	v_lshrrev_b32_e32 v38, 3, v36
	v_lshlrev_b32_e32 v37, 6, v36
	v_and_or_b32 v38, v38, 12, s64
	v_lshlrev_b32_e32 v39, 2, v36
	v_and_or_b32 v37, v37, s15, v142
	v_lshlrev_b32_e32 v38, 10, v38
	v_and_b32_e32 v39, 32, v39
	v_bitop3_b32 v132, v37, v38, v39 bitop3:0xde
	v_mul_f32_e32 v38, 0xbfb8aa3b, v32
	v_mul_f32_e32 v39, 0xbfb8aa3b, v33
	v_exp_f32_e32 v38, v38
	v_exp_f32_e32 v39, v39
	v_lshlrev_b32_e32 v36, 7, v36
	v_and_b32_e32 v36, 0x4000, v36
	v_add_f32_e32 v38, 1.0, v38
	v_add_f32_e32 v39, 1.0, v39
	v_rcp_f32_e32 v38, v38
	v_rcp_f32_e32 v39, v39
	v_mov_b32_e32 v37, v133
	v_lshl_add_u64 v[36:37], v[68:69], 0, v[36:37]
	v_lshl_add_u64 v[36:37], v[36:37], 0, v[132:133]
	v_pk_mul_f32 v[32:33], v[32:33], v[38:39]
	global_store_dwordx4 v[52:53], v[44:47], off
	v_pk_mul_f32 v[28:29], v[32:33], v[28:29]
	s_nop 0
	v_cvt_pk_bf16_f32 v28, v28, v29
	v_mul_f32_e32 v29, 0xbfb8aa3b, v34
	v_exp_f32_e32 v29, v29
	s_nop 0
	v_add_f32_e32 v29, 1.0, v29
	v_rcp_f32_e32 v32, v29
	v_mul_f32_e32 v29, 0xbfb8aa3b, v35
	v_exp_f32_e32 v29, v29
	s_nop 0
	v_add_f32_e32 v29, 1.0, v29
	v_rcp_f32_e32 v33, v29
	s_nop 0
	v_pk_mul_f32 v[32:33], v[34:35], v[32:33]
	s_nop 0
	v_pk_mul_f32 v[30:31], v[32:33], v[30:31]
	s_nop 0
	v_cvt_pk_bf16_f32 v29, v30, v31
	v_mul_f32_e32 v30, 0xbfb8aa3b, v24
	v_mul_f32_e32 v31, 0xbfb8aa3b, v25
	v_exp_f32_e32 v30, v30
	v_exp_f32_e32 v31, v31
	v_add_f32_e32 v30, 1.0, v30
	v_add_f32_e32 v31, 1.0, v31
	v_rcp_f32_e32 v30, v30
	v_rcp_f32_e32 v31, v31
	s_nop 0
	v_pk_mul_f32 v[24:25], v[24:25], v[30:31]
	s_nop 0
	v_pk_mul_f32 v[20:21], v[24:25], v[20:21]
	s_nop 0
	v_cvt_pk_bf16_f32 v30, v20, v21
	v_mul_f32_e32 v20, 0xbfb8aa3b, v26
	v_mul_f32_e32 v21, 0xbfb8aa3b, v27
	v_exp_f32_e32 v20, v20
	v_exp_f32_e32 v21, v21
	v_add_f32_e32 v20, 1.0, v20
	v_add_f32_e32 v21, 1.0, v21
	v_rcp_f32_e32 v20, v20
	v_rcp_f32_e32 v21, v21
	s_nop 0
	v_pk_mul_f32 v[20:21], v[26:27], v[20:21]
	s_nop 0
	v_pk_mul_f32 v[20:21], v[20:21], v[22:23]
	s_nop 0
	v_cvt_pk_bf16_f32 v31, v20, v21
	v_add_u32_e32 v20, 0xb0, v145
	v_lshrrev_b32_e32 v22, 3, v20
	v_lshlrev_b32_e32 v21, 6, v20
	v_and_or_b32 v22, v22, 14, s64
	v_lshlrev_b32_e32 v23, 2, v20
	v_and_or_b32 v21, v21, s15, v142
	v_lshlrev_b32_e32 v22, 10, v22
	v_and_b32_e32 v23, 32, v23
	v_bitop3_b32 v132, v21, v22, v23 bitop3:0xde
	v_mul_f32_e32 v22, 0xbfb8aa3b, v16
	v_mul_f32_e32 v23, 0xbfb8aa3b, v17
	v_exp_f32_e32 v22, v22
	v_exp_f32_e32 v23, v23
	v_lshlrev_b32_e32 v20, 7, v20
	v_and_b32_e32 v20, 0x4000, v20
	v_add_f32_e32 v22, 1.0, v22
	v_add_f32_e32 v23, 1.0, v23
	v_rcp_f32_e32 v22, v22
	v_rcp_f32_e32 v23, v23
	v_mov_b32_e32 v21, v133
	v_lshl_add_u64 v[20:21], v[68:69], 0, v[20:21]
	v_lshl_add_u64 v[20:21], v[20:21], 0, v[132:133]
	v_pk_mul_f32 v[16:17], v[16:17], v[22:23]
	global_store_dwordx4 v[36:37], v[28:31], off
	v_pk_mul_f32 v[12:13], v[16:17], v[12:13]
	s_nop 0
	v_cvt_pk_bf16_f32 v12, v12, v13
	v_mul_f32_e32 v13, 0xbfb8aa3b, v18
	v_exp_f32_e32 v13, v13
	s_nop 0
	v_add_f32_e32 v13, 1.0, v13
	v_rcp_f32_e32 v16, v13
	v_mul_f32_e32 v13, 0xbfb8aa3b, v19
	v_exp_f32_e32 v13, v13
	s_nop 0
	v_add_f32_e32 v13, 1.0, v13
	v_rcp_f32_e32 v17, v13
	s_nop 0
	v_pk_mul_f32 v[16:17], v[18:19], v[16:17]
	s_nop 0
	v_pk_mul_f32 v[14:15], v[16:17], v[14:15]
	s_nop 0
	v_cvt_pk_bf16_f32 v13, v14, v15
	v_mul_f32_e32 v14, 0xbfb8aa3b, v8
	v_mul_f32_e32 v15, 0xbfb8aa3b, v9
	v_exp_f32_e32 v14, v14
	v_exp_f32_e32 v15, v15
	v_add_f32_e32 v14, 1.0, v14
	v_add_f32_e32 v15, 1.0, v15
	v_rcp_f32_e32 v14, v14
	v_rcp_f32_e32 v15, v15
	s_nop 0
	v_pk_mul_f32 v[8:9], v[8:9], v[14:15]
	s_nop 0
	v_pk_mul_f32 v[4:5], v[8:9], v[4:5]
	s_nop 0
	v_cvt_pk_bf16_f32 v14, v4, v5
	v_mul_f32_e32 v4, 0xbfb8aa3b, v10
	v_mul_f32_e32 v5, 0xbfb8aa3b, v11
	v_exp_f32_e32 v4, v4
	v_exp_f32_e32 v5, v5
	v_add_f32_e32 v4, 1.0, v4
	v_add_f32_e32 v5, 1.0, v5
	v_rcp_f32_e32 v4, v4
	v_rcp_f32_e32 v5, v5
	s_nop 0
	v_pk_mul_f32 v[4:5], v[10:11], v[4:5]
	s_nop 0
	v_pk_mul_f32 v[4:5], v[4:5], v[6:7]
	s_nop 0
	v_cvt_pk_bf16_f32 v15, v4, v5
	global_store_dwordx4 v[20:21], v[12:15], off
	s_cbranch_vccz .LBB0_892
	s_waitcnt vmcnt(0)
	s_cmpk_gt_u32 s2, 0xff
	s_cbranch_scc1 .LBB0_903
	s_barrier
